# remaining LDS swizzle butterflies (attention A epilogue, P2 prelude, P0) -> DPP quad_perm/row mirrors + permlane16_swap; tile-start accumulator zeroing with v_mov_b64
# speedup vs baseline: 1.0049x; 1.0016x over previous
; __device__ __forceinline__ unsigned cvtpk(float lo, float hi) { f32x2 v = {lo, hi}; bf16x2_t b = __builtin_convertvector(v, bf16x2_t); return __builtin_bit_cast(unsigned, b); }
; __device__ __forceinline__ float wave_sum(float v) { v = bfly_add<1>(v); v = bfly_add<2>(v); v = bfly_add<4>(v); v = bfly_add<8>(v); v = bfly_add<16>(v); v = bfly_add<32>(v); return v; }
; __device__ __forceinline__ void raw_rows_to_bf16(const float* xa, const float* xb, bf16_t* oa, bf16_t* ob, float* psa, float* psb, int lane, bool two) {
;     const f32x4* ra = (const f32x4*)xa + lane; const f32x4* rb = (const f32x4*)xb + lane;
;     f32x4 va[4], vb[4]; float sa = 0.f, sb = 0.f;
; #pragma unroll
;     for (int j = 0; j < 4; ++j) { va[j] = ra[64 * j]; vb[j] = rb[64 * j]; }
; #pragma unroll
;     for (int j = 0; j < 4; ++j) { sa += (va[j][0] * va[j][0] + va[j][1] * va[j][1]) + (va[j][2] * va[j][2] + va[j][3] * va[j][3]); sb += (vb[j][0] * vb[j][0] + vb[j][1] * vb[j][1]) + (vb[j][2] * vb[j][2] + vb[j][3] * vb[j][3]); }
;     sa = wave_sum(sa); sb = wave_sum(sb);
;     u32x2* pa = (u32x2*)oa + lane; u32x2* pb = (u32x2*)ob + lane;
; #pragma unroll
;     for (int j = 0; j < 4; ++j) { u32x2 w; w.x = cvtpk(va[j][0], va[j][1]); w.y = cvtpk(va[j][2], va[j][3]); pa[64 * j] = w;
;         if (two) { w.x = cvtpk(vb[j][0], vb[j][1]); w.y = cvtpk(vb[j][2], vb[j][3]); pb[64 * j] = w; } }
;     if (lane < 16) { psa[lane] = lane == 0 ? sa : 0.f; if (two) psb[lane] = lane == 0 ? sb : 0.f; }
; }
; __global__ void __launch_bounds__(NTHREADS, 2) hymba_fwd(Args args) {
;     ...
;         for (int m = gw; m < MT; m += 2 * NGW) {
;             const int m2 = m + NGW;
;             const float* xa = m < MP ? ap_->in[I_XP] + (size_t)m * DM : ap_->in[I_XS] + (size_t)(m - MP) * DM;
;             const float* xb = m2 < MP ? ap_->in[I_XP] + (size_t)m2 * DM : ap_->in[I_XS] + (size_t)((m2 < MT ? m2 : m) - MP) * DM;
;             raw_rows_to_bf16(xa, xb, XN + (size_t)m * DM, XN + (size_t)(m2 < MT ? m2 : m) * DM, PS + (size_t)m * 16, PS + (size_t)(m2 < MT ? m2 : m) * 16, lane, m2 < MT); }
.LBB0_72:
	s_add_i32 s13, s16, s14
	s_add_i32 s6, s16, 0xffff0000
	s_ashr_i32 s17, s16, 31
	s_cmp_lt_i32 s16, 0x10000
	s_cselect_b32 s15, 0, 8
	s_cselect_b32 s7, s17, 0
	s_cselect_b32 s6, s16, s6
	s_add_u32 s18, s2, s15
	s_addc_u32 s19, s3, 0
	s_load_dwordx2 s[18:19], s[18:19], 0x0
	s_lshl_b64 s[6:7], s[6:7], 12
	s_waitcnt lgkmcnt(0)
	s_add_u32 s6, s18, s6
	s_addc_u32 s7, s19, s7
	s_cmp_lt_u32 s13, 0x14000
	global_load_dwordx4 v[42:45], v1, s[6:7]
	global_load_dwordx4 v[18:21], v1, s[6:7] offset:1024
	global_load_dwordx4 v[10:13], v1, s[6:7] offset:2048
	global_load_dwordx4 v[2:5], v1, s[6:7] offset:3072
	s_cselect_b32 s6, s13, s16
	s_add_i32 s6, s6, 0xffff0000
	s_cmp_lt_i32 s13, 0x10000
	s_cselect_b32 s7, 0, 8
	s_cselect_b32 s6, s13, s6
	s_add_u32 s18, s2, s7
	s_addc_u32 s19, s3, 0
	s_load_dwordx2 s[18:19], s[18:19], 0x0
	s_ashr_i32 s7, s6, 31
	s_lshl_b64 s[6:7], s[6:7], 12
	s_waitcnt lgkmcnt(0)
	s_add_u32 s6, s18, s6
	s_addc_u32 s7, s19, s7
	global_load_dwordx4 v[26:29], v1, s[6:7]
	global_load_dwordx4 v[22:25], v1, s[6:7] offset:1024
	global_load_dwordx4 v[14:17], v1, s[6:7] offset:2048
	global_load_dwordx4 v[6:9], v1, s[6:7] offset:3072
	s_lshl_b64 s[18:19], s[16:17], 11
	s_cmp_lt_i32 s13, 0x14000
	s_cselect_b64 s[20:21], -1, 0
	s_and_b64 s[6:7], s[20:21], exec
	s_cselect_b32 s22, s13, s16
	s_ashr_i32 s23, s22, 31
	s_lshl_b64 s[24:25], s[22:23], 11
	v_lshl_add_u64 v[38:39], v[34:35], 0, s[18:19]
	s_cmp_gt_i32 s13, 0x13fff
	s_waitcnt vmcnt(7)
	v_mul_f32_e32 v33, v43, v43
	v_mul_f32_e32 v40, v45, v45
	s_waitcnt vmcnt(6)
	v_mul_f32_e32 v41, v19, v19
	v_mul_f32_e32 v46, v21, v21
	s_waitcnt vmcnt(5)
	v_mul_f32_e32 v47, v11, v11
	v_mul_f32_e32 v48, v13, v13
	v_fmac_f32_e32 v33, v42, v42
	v_fmac_f32_e32 v40, v44, v44
	v_fmac_f32_e32 v41, v18, v18
	v_fmac_f32_e32 v46, v20, v20
	s_waitcnt vmcnt(4)
	v_mul_f32_e32 v49, v3, v3
	v_mul_f32_e32 v50, v5, v5
	v_fmac_f32_e32 v47, v10, v10
	v_fmac_f32_e32 v48, v12, v12
	v_add_f32_e32 v33, v33, v40
	v_add_f32_e32 v40, v41, v46
	v_fmac_f32_e32 v49, v2, v2
	v_fmac_f32_e32 v50, v4, v4
	v_add_f32_e32 v41, v47, v48
	v_add_f32_e32 v33, v33, v40
	v_add_f32_e32 v46, v49, v50
	v_add_f32_e32 v33, v33, v41
	v_add_f32_e32 v33, v33, v46
	s_waitcnt vmcnt(3)
	v_mul_f32_e32 v41, v27, v27
	v_mul_f32_e32 v46, v29, v29
	s_waitcnt vmcnt(2)
	v_mul_f32_e32 v47, v23, v23
	v_mul_f32_e32 v48, v25, v25
	s_waitcnt vmcnt(1)
	v_mul_f32_e32 v49, v15, v15
	v_mul_f32_e32 v50, v17, v17
	v_fmac_f32_e32 v41, v26, v26
	v_fmac_f32_e32 v46, v28, v28
	v_fmac_f32_e32 v47, v22, v22
	v_fmac_f32_e32 v48, v24, v24
	s_waitcnt vmcnt(0)
	v_mul_f32_e32 v51, v7, v7
	v_mul_f32_e32 v52, v9, v9
	v_fmac_f32_e32 v49, v14, v14
	v_fmac_f32_e32 v50, v16, v16
	v_add_f32_e32 v41, v41, v46
	v_add_f32_e32 v46, v47, v48
	v_fmac_f32_e32 v51, v6, v6
	v_fmac_f32_e32 v52, v8, v8
	v_add_f32_e32 v47, v49, v50
	v_add_f32_e32 v41, v41, v46
	v_add_f32_e32 v48, v51, v52
	v_add_f32_e32 v41, v41, v47
	v_add_f32_e32 v41, v41, v48
	s_nop 1
	v_mov_b32_dpp v40, v33 quad_perm:[1,0,3,2] row_mask:0xf bank_mask:0xf
	s_nop 1
	v_mov_b32_dpp v46, v41 quad_perm:[1,0,3,2] row_mask:0xf bank_mask:0xf
	s_waitcnt lgkmcnt(0)
	v_add_f32_e32 v33, v33, v40
	s_waitcnt lgkmcnt(0)
	v_add_f32_e32 v41, v41, v46
	s_nop 1
	v_mov_b32_dpp v40, v33 quad_perm:[2,3,0,1] row_mask:0xf bank_mask:0xf
	s_nop 1
	v_mov_b32_dpp v46, v41 quad_perm:[2,3,0,1] row_mask:0xf bank_mask:0xf
	s_waitcnt lgkmcnt(0)
	v_add_f32_e32 v33, v33, v40
	s_waitcnt lgkmcnt(0)
	v_add_f32_e32 v46, v41, v46
	s_nop 1
	v_mov_b32_dpp v40, v33 row_half_mirror row_mask:0xf bank_mask:0xf
	s_nop 1
	v_mov_b32_dpp v47, v46 row_half_mirror row_mask:0xf bank_mask:0xf
	s_waitcnt lgkmcnt(0)
	v_add_f32_e32 v33, v33, v40
	s_waitcnt lgkmcnt(0)
	v_add_f32_e32 v49, v46, v47
	s_nop 1
	v_mov_b32_dpp v48, v33 row_mirror row_mask:0xf bank_mask:0xf
	s_nop 1
	v_mov_b32_dpp v50, v49 row_mirror row_mask:0xf bank_mask:0xf
	v_cvt_pk_bf16_f32 v46, v42, v43
	v_cvt_pk_bf16_f32 v47, v44, v45
	v_lshl_add_u64 v[40:41], v[34:35], 0, s[24:25]
	s_waitcnt lgkmcnt(0)
	v_add_f32_e32 v33, v33, v48
	s_waitcnt lgkmcnt(0)
	v_add_f32_e32 v42, v49, v50
	v_mov_b32_e32 v48, v33
	s_nop 1
	v_permlane16_swap_b32_e32 v33, v48
	v_mov_b32_e32 v45, v42
	s_nop 1
	v_permlane16_swap_b32_e32 v42, v45
	global_store_dwordx2 v[38:39], v[46:47], off
	s_waitcnt lgkmcnt(0)
	v_add_f32_e32 v43, v33, v48
	s_waitcnt lgkmcnt(0)
	v_add_f32_e32 v33, v42, v45
	v_mov_b32_e32 v44, v43
	v_mov_b32_e32 v42, v33
	s_nop 0
	v_permlane32_swap_b32_e32 v43, v44
	v_permlane32_swap_b32_e32 v33, v42
	s_cbranch_scc1 .LBB0_74
	v_cvt_pk_bf16_f32 v26, v26, v27
	v_cvt_pk_bf16_f32 v27, v28, v29
	v_cvt_pk_bf16_f32 v18, v18, v19
	v_cvt_pk_bf16_f32 v19, v20, v21
	s_mov_b64 s[6:7], s[24:25]
	global_store_dwordx2 v[40:41], v[26:27], off
	global_store_dwordx2 v[38:39], v[18:19], off offset:512
	s_branch .LBB0_75

; __device__ __forceinline__ unsigned cvtpk(float lo, float hi) { f32x2 v = {lo, hi}; bf16x2_t b = __builtin_convertvector(v, bf16x2_t); return __builtin_bit_cast(unsigned, b); }
; __device__ __forceinline__ float wave_sum(float v) { v = bfly_add<1>(v); v = bfly_add<2>(v); v = bfly_add<4>(v); v = bfly_add<8>(v); v = bfly_add<16>(v); v = bfly_add<32>(v); return v; }
; __device__ __forceinline__ void rms_row_to_bf16(const float* xrow, const float* g, bf16_t* orow, int lane) {
;     const f32x4* xr = (const f32x4*)xrow + lane; const f32x4* gr = (const f32x4*)g + lane;
;     f32x4 v[4]; float s = 0.f;
; #pragma unroll
;     for (int j = 0; j < 4; ++j) { v[j] = xr[64 * j]; s += (v[j][0] * v[j][0] + v[j][1] * v[j][1]) + (v[j][2] * v[j][2] + v[j][3] * v[j][3]); }
;     const float rstd = rsqrtf(wave_sum(s) * (1.f / DM) + EPS);
;     u32x2* o8 = (u32x2*)orow + lane;
; #pragma unroll
;     for (int j = 0; j < 4; ++j) { const f32x4 gg = g ? gr[64 * j] : (f32x4){1.f, 1.f, 1.f, 1.f}; u32x2 w; w.x = cvtpk(v[j][0] * rstd * gg[0], v[j][1] * rstd * gg[1]); w.y = cvtpk(v[j][2] * rstd * gg[2], v[j][3] * rstd * gg[3]); o8[64 * j] = w; }
; }
; __global__ void __launch_bounds__(NTHREADS, 2) hymba_fwd(Args args) {
;     ...
;         for (int m = gw; m < 2 * MMEM; m += NGW) { const int l = m / MMEM, r = m - l * MMEM; const float* xr = r < NBATCH * MEMT ? ap_->in[I_MEMP] + (size_t)r * DM : ap_->in[I_MEMS] + (size_t)(r - NBATCH * MEMT) * DM;
;             rms_row_to_bf16(xr, ap_->in[I_MEMG] + l * DM, XNM + (size_t)m * DM, lane); }
.LBB0_84:
	s_ashr_i32 s9, s12, 31
	s_lshr_b32 s9, s9, 20
	s_add_i32 s9, s12, s9
	s_ashr_i32 s20, s9, 12
	s_and_b32 s9, s9, 0xfffff000
	s_sub_i32 s16, s12, s9
	s_add_i32 s18, s16, 0xfffff800
	s_ashr_i32 s17, s9, 31
	s_sub_u32 s9, s12, s9
	s_subb_u32 s17, s13, s17
	s_cmpk_lt_i32 s16, 0x800
	s_cselect_b32 s16, s9, s18
	s_cselect_b32 s9, 16, 24
	s_cselect_b32 s17, s17, 0
	s_add_u32 s18, s2, s9
	s_addc_u32 s19, s3, 0
	s_load_dwordx2 s[18:19], s[18:19], 0x0
	s_lshl_b64 s[16:17], s[16:17], 12
	s_waitcnt lgkmcnt(0)
	s_add_u32 s16, s18, s16
	s_addc_u32 s17, s19, s17
	global_load_dwordx4 v[14:17], v1, s[16:17]
	global_load_dwordx4 v[10:13], v1, s[16:17] offset:1024
	global_load_dwordx4 v[6:9], v1, s[16:17] offset:2048
	global_load_dwordx4 v[2:5], v1, s[16:17] offset:3072
	s_lshl_b32 s16, s20, 10
	s_ashr_i32 s17, s16, 31
	s_and_b64 vcc, exec, s[4:5]
	s_waitcnt vmcnt(3)
	v_mul_f32_e32 v18, v15, v15
	v_mul_f32_e32 v19, v17, v17
	s_waitcnt vmcnt(2)
	v_mul_f32_e32 v20, v11, v11
	v_mul_f32_e32 v21, v13, v13
	s_waitcnt vmcnt(1)
	v_mul_f32_e32 v22, v7, v7
	v_mul_f32_e32 v23, v9, v9
	v_fmac_f32_e32 v18, v14, v14
	v_fmac_f32_e32 v19, v16, v16
	v_fmac_f32_e32 v20, v10, v10
	v_fmac_f32_e32 v21, v12, v12
	s_waitcnt vmcnt(0)
	v_mul_f32_e32 v28, v3, v3
	v_mul_f32_e32 v29, v5, v5
	v_fmac_f32_e32 v22, v6, v6
	v_fmac_f32_e32 v23, v8, v8
	v_add_f32_e32 v18, v18, v19
	v_add_f32_e32 v19, v20, v21
	v_fmac_f32_e32 v28, v2, v2
	v_fmac_f32_e32 v29, v4, v4
	v_add_f32_e32 v20, v22, v23
	v_add_f32_e32 v18, v18, v19
	v_add_f32_e32 v21, v28, v29
	v_add_f32_e32 v18, v18, v20
	v_add_f32_e32 v18, v18, v21
	s_nop 1
	v_mov_b32_dpp v19, v18 quad_perm:[1,0,3,2] row_mask:0xf bank_mask:0xf
	v_mov_b32_e32 v20, 1.0
	v_mov_b32_e32 v21, 1.0
	v_mov_b32_e32 v22, 1.0
	v_lshl_add_u64 v[28:29], s[16:17], 2, v[24:25]
	s_waitcnt lgkmcnt(0)
	v_add_f32_e32 v18, v18, v19
	s_nop 1
	v_mov_b32_dpp v19, v18 quad_perm:[2,3,0,1] row_mask:0xf bank_mask:0xf
	s_waitcnt lgkmcnt(0)
	v_add_f32_e32 v18, v18, v19
	s_nop 1
	v_mov_b32_dpp v19, v18 row_half_mirror row_mask:0xf bank_mask:0xf
	s_waitcnt lgkmcnt(0)
	v_add_f32_e32 v19, v18, v19
	s_nop 1
	v_mov_b32_dpp v23, v19 row_mirror row_mask:0xf bank_mask:0xf
	v_mov_b32_e32 v18, 1.0
	s_waitcnt lgkmcnt(0)
	v_add_f32_e32 v19, v19, v23
	v_mov_b32_e32 v23, v19
	s_nop 1
	v_permlane16_swap_b32_e32 v19, v23
	s_waitcnt lgkmcnt(0)
	v_add_f32_e32 v19, v19, v23
	v_mov_b32_e32 v32, v19
	s_nop 1
	v_permlane32_swap_b32_e32 v19, v32
	v_mov_b32_e32 v23, 1.0
	s_cbranch_vccnz .LBB0_86
	global_load_dwordx4 v[20:23], v[28:29], off

; #define PG8_ABASE(pm_) (HALO ? ((const char*)Ag + ((long)halo_row0(pm_)) * (long)K * 2) : ((const char*)Ag + (size_t)(pm_) * 2 * hstepB))
; template <class Epi, bool HALO>
; __device__ __forceinline__ void gemm_phase(LAS unsigned char* lds, const bf16_t* Ag, const bf16_t* Btg, const int K, const int nM, const int nN, const int G, const int cidx, const int wave_, const Epi& E) {
;     ...
;         const bool has_next = S.next(ui + 1, nxt);
;         const char* nA = has_next ? PG8_ABASE(nxt.pm) : cA; const char* nB = has_next ? PG8_BBASE(nxt.pn) : cB;
;         for (int t = 0; t < nt; t += 2) {
;             const bool last = (t == nt - 2);
;             const char* a1 = cA + (size_t)(t + 1) * kstep;
;             const char* a2 = last ? nA : cA + (size_t)(t + 2) * kstep; const char* b2 = last ? nB : cB + (size_t)(t + 2) * kstep;
;     ...
; #pragma unroll
;         for (int a = 0; a < 2; ++a)
; #pragma unroll
;             for (int b = 0; b < 2; ++b)
; #pragma unroll
;                 for (int m = 0; m < 4; ++m)
; #pragma unroll
;                     for (int n = 0; n < 2; ++n) acc[a][b][m][n] = (f32x4){0.f, 0.f, 0.f, 0.f};
.LBB0_148:
	s_ashr_i32 s21, s20, 31
	s_lshl_b64 s[22:23], s[20:21], 19
	s_add_u32 s22, s28, s22
	s_addc_u32 s23, s29, s23
	s_and_b64 s[24:25], s[6:7], exec
	s_cselect_b32 s21, s23, s5
	s_cselect_b32 s41, s22, s4
	s_ashr_i32 s19, s18, 31
	s_lshl_b64 s[24:25], s[18:19], 19
	s_add_u32 s24, s0, s24
	s_addc_u32 s25, s1, s25
	s_and_b64 s[26:27], s[6:7], exec
	s_cselect_b32 s19, s25, s9
	s_cselect_b32 s42, s24, s8
	s_add_u32 s4, s4, 0x40080
	s_addc_u32 s5, s5, 0
	s_add_u32 s43, s8, 0x100
	v_mov_b32_e32 v0, 0
	s_addc_u32 s44, s9, 0
	s_mov_b32 s45, -2
	v_mov_b64_e32 v[0:1], 0
	v_mov_b64_e32 v[2:3], 0
	v_mov_b64_e32 v[4:5], 0
	v_mov_b64_e32 v[6:7], 0
	v_mov_b64_e32 v[8:9], 0
	v_mov_b64_e32 v[10:11], 0
	v_mov_b64_e32 v[12:13], 0
	v_mov_b64_e32 v[14:15], 0
	v_mov_b64_e32 v[16:17], 0
	v_mov_b64_e32 v[18:19], 0
	v_mov_b64_e32 v[20:21], 0
	v_mov_b64_e32 v[22:23], 0
	v_mov_b64_e32 v[24:25], 0
	v_mov_b64_e32 v[26:27], 0
	v_mov_b64_e32 v[28:29], 0
	v_mov_b64_e32 v[30:31], 0
	v_mov_b64_e32 v[32:33], 0
	v_mov_b64_e32 v[34:35], 0
	v_mov_b64_e32 v[36:37], 0
	v_mov_b64_e32 v[38:39], 0
	v_mov_b64_e32 v[40:41], 0
	v_mov_b64_e32 v[42:43], 0
	v_mov_b64_e32 v[44:45], 0
	v_mov_b64_e32 v[46:47], 0
	v_mov_b64_e32 v[48:49], 0
	v_mov_b64_e32 v[50:51], 0
	v_mov_b64_e32 v[52:53], 0
	v_mov_b64_e32 v[54:55], 0
	v_mov_b64_e32 v[56:57], 0
	v_mov_b64_e32 v[58:59], 0
	v_mov_b64_e32 v[60:61], 0
	v_mov_b64_e32 v[62:63], 0
	v_mov_b64_e32 v[80:81], 0
	v_mov_b64_e32 v[82:83], 0
	v_mov_b64_e32 v[84:85], 0
	v_mov_b64_e32 v[86:87], 0
	v_mov_b64_e32 v[88:89], 0
	v_mov_b64_e32 v[90:91], 0
	v_mov_b64_e32 v[92:93], 0
	v_mov_b64_e32 v[94:95], 0
	v_mov_b64_e32 v[96:97], 0
	v_mov_b64_e32 v[98:99], 0
	v_mov_b64_e32 v[100:101], 0
	v_mov_b64_e32 v[102:103], 0
	v_mov_b64_e32 v[104:105], 0
	v_mov_b64_e32 v[106:107], 0
	v_mov_b64_e32 v[108:109], 0
	v_mov_b64_e32 v[110:111], 0
	v_mov_b64_e32 v[112:113], 0
	v_mov_b64_e32 v[114:115], 0
	v_mov_b64_e32 v[116:117], 0
	v_mov_b64_e32 v[118:119], 0
	v_mov_b64_e32 v[120:121], 0
	v_mov_b64_e32 v[122:123], 0
	v_mov_b64_e32 v[124:125], 0
	v_mov_b64_e32 v[126:127], 0
	v_mov_b64_e32 v[128:129], 0
	v_mov_b64_e32 v[130:131], 0
	v_mov_b64_e32 v[132:133], 0
	v_mov_b64_e32 v[134:135], 0
	v_mov_b64_e32 v[136:137], 0
	v_mov_b64_e32 v[138:139], 0
	v_mov_b64_e32 v[140:141], 0
	v_mov_b64_e32 v[142:143], 0

; #define PG8_ABASE(pm_) (HALO ? ((const char*)Ag + ((long)halo_row0(pm_)) * (long)K * 2) : ((const char*)Ag + (size_t)(pm_) * 2 * hstepB))
; template <class Epi, bool HALO>
; __device__ __forceinline__ void gemm_phase(LAS unsigned char* lds, const bf16_t* Ag, const bf16_t* Btg, const int K, const int nM, const int nN, const int G, const int cidx, const int wave_, const Epi& E) {
;     ...
;         const bool has_next = S.next(ui + 1, nxt);
;         const char* nA = has_next ? PG8_ABASE(nxt.pm) : cA; const char* nB = has_next ? PG8_BBASE(nxt.pn) : cB;
;         for (int t = 0; t < nt; t += 2) {
;             const bool last = (t == nt - 2);
;             const char* a1 = cA + (size_t)(t + 1) * kstep;
;             const char* a2 = last ? nA : cA + (size_t)(t + 2) * kstep; const char* b2 = last ? nB : cB + (size_t)(t + 2) * kstep;
;     ...
; #pragma unroll
;         for (int a = 0; a < 2; ++a)
; #pragma unroll
;             for (int b = 0; b < 2; ++b)
; #pragma unroll
;                 for (int m = 0; m < 4; ++m)
; #pragma unroll
;                     for (int n = 0; n < 2; ++n) acc[a][b][m][n] = (f32x4){0.f, 0.f, 0.f, 0.f};
.LBB0_192:
	s_ashr_i32 s15, s14, 31
	s_lshl_b64 s[16:17], s[14:15], 19
	s_add_u32 s16, s24, s16
	s_addc_u32 s17, s25, s17
	s_and_b64 s[18:19], s[2:3], exec
	s_cselect_b32 s15, s17, s5
	s_cselect_b32 s38, s16, s4
	s_ashr_i32 s13, s12, 31
	s_lshl_b64 s[18:19], s[12:13], 19
	s_add_u32 s18, s0, s18
	s_addc_u32 s19, s1, s19
	s_and_b64 s[22:23], s[2:3], exec
	s_cselect_b32 s13, s19, s21
	s_cselect_b32 s39, s18, s20
	s_add_u32 s4, s4, 0x40080
	s_addc_u32 s5, s5, 0
	s_add_u32 s40, s20, 0x100
	v_mov_b32_e32 v0, 0
	s_addc_u32 s41, s21, 0
	s_mov_b32 s42, -2
	v_mov_b64_e32 v[0:1], 0
	v_mov_b64_e32 v[2:3], 0
	v_mov_b64_e32 v[4:5], 0
	v_mov_b64_e32 v[6:7], 0
	v_mov_b64_e32 v[8:9], 0
	v_mov_b64_e32 v[10:11], 0
	v_mov_b64_e32 v[12:13], 0
	v_mov_b64_e32 v[14:15], 0
	v_mov_b64_e32 v[16:17], 0
	v_mov_b64_e32 v[18:19], 0
	v_mov_b64_e32 v[20:21], 0
	v_mov_b64_e32 v[22:23], 0
	v_mov_b64_e32 v[24:25], 0
	v_mov_b64_e32 v[26:27], 0
	v_mov_b64_e32 v[28:29], 0
	v_mov_b64_e32 v[30:31], 0
	v_mov_b64_e32 v[32:33], 0
	v_mov_b64_e32 v[34:35], 0
	v_mov_b64_e32 v[36:37], 0
	v_mov_b64_e32 v[38:39], 0
	v_mov_b64_e32 v[40:41], 0
	v_mov_b64_e32 v[42:43], 0
	v_mov_b64_e32 v[44:45], 0
	v_mov_b64_e32 v[46:47], 0
	v_mov_b64_e32 v[48:49], 0
	v_mov_b64_e32 v[50:51], 0
	v_mov_b64_e32 v[52:53], 0
	v_mov_b64_e32 v[54:55], 0
	v_mov_b64_e32 v[56:57], 0
	v_mov_b64_e32 v[58:59], 0
	v_mov_b64_e32 v[60:61], 0
	v_mov_b64_e32 v[62:63], 0
	v_mov_b64_e32 v[64:65], 0
	v_mov_b64_e32 v[66:67], 0
	v_mov_b64_e32 v[68:69], 0
	v_mov_b64_e32 v[70:71], 0
	v_mov_b64_e32 v[72:73], 0
	v_mov_b64_e32 v[74:75], 0
	v_mov_b64_e32 v[76:77], 0
	v_mov_b64_e32 v[78:79], 0
	v_mov_b64_e32 v[80:81], 0
	v_mov_b64_e32 v[82:83], 0
	v_mov_b64_e32 v[84:85], 0
	v_mov_b64_e32 v[86:87], 0
	v_mov_b64_e32 v[88:89], 0
	v_mov_b64_e32 v[90:91], 0
	v_mov_b64_e32 v[92:93], 0
	v_mov_b64_e32 v[94:95], 0
	v_mov_b64_e32 v[112:113], 0
	v_mov_b64_e32 v[114:115], 0
	v_mov_b64_e32 v[116:117], 0
	v_mov_b64_e32 v[118:119], 0
	v_mov_b64_e32 v[120:121], 0
	v_mov_b64_e32 v[122:123], 0
	v_mov_b64_e32 v[124:125], 0
	v_mov_b64_e32 v[126:127], 0
	v_mov_b64_e32 v[128:129], 0
	v_mov_b64_e32 v[130:131], 0
	v_mov_b64_e32 v[132:133], 0
	v_mov_b64_e32 v[134:135], 0
	v_mov_b64_e32 v[136:137], 0
	v_mov_b64_e32 v[138:139], 0
	v_mov_b64_e32 v[140:141], 0
	v_mov_b64_e32 v[142:143], 0

; __device__ __forceinline__ float wave_sum(float v) { v = bfly_add<1>(v); v = bfly_add<2>(v); v = bfly_add<4>(v); v = bfly_add<8>(v); v = bfly_add<16>(v); v = bfly_add<32>(v); return v; }
; __device__ __forceinline__ float wave_max(float v) { v = bfly_max<1>(v); v = bfly_max<2>(v); v = bfly_max<4>(v); v = bfly_max<8>(v); v = bfly_max<16>(v); v = bfly_max<32>(v); return v; }
; __global__ void __launch_bounds__(NTHREADS, 2) hymba_fwd(Args args) {
;     ...
;             if (wave == 0) { const float a = wave_sum(ap_->in[I_LQ1][l * 64 + lane] * ap_->in[I_LK1][l * 64 + lane]), b = wave_sum(ap_->in[I_LQ2][l * 64 + lane] * ap_->in[I_LK2][l * 64 + lane]);
;                 const float lam_init = 0.8f - 0.6f * expf(-0.3f * (float)l); if (lane == 0) { misc[0] = expf(a) - expf(b) + lam_init; misc[1] = 1.f - lam_init; }
;                 auto wmax = [&](float v) { return wave_max(fabsf(v)); };
;                 const float gqa = wmax(ap_->in[I_QNA][l * 64 + lane]), gka = wmax(ap_->in[I_KNA][l * 64 + lane]), gqb = wmax(ap_->in[I_QNB][l * 64 + lane]), gkb = wmax(ap_->in[I_KNB][l * 64 + lane]);
;                 const float gqc = wmax(ap_->in[I_QNC][l * 64 + lane]), gkc = wmax(ap_->in[I_KNC][l * 64 + lane]);
.LBB0_293:
	s_or_b64 exec, exec, s[6:7]
	v_readlane_b32 s4, v254, 8
	v_readlane_b32 s5, v254, 9
	s_and_b64 vcc, exec, s[4:5]
	s_cbranch_vccz .LBB0_305
	s_waitcnt lgkmcnt(0)
	s_load_dwordx8 s[4:11], s[2:3], 0x40
	v_and_b32_e32 v0, 63, v0
	v_readlane_b32 s12, v255, 4
	v_cmp_eq_u32_e32 vcc, 0, v0
	v_readlane_b32 s13, v255, 5
	v_lshl_or_b32 v144, s12, 6, v0
	v_lshlrev_b64 v[2:3], 2, v[144:145]
	s_waitcnt lgkmcnt(0)
	v_lshl_add_u64 v[4:5], s[4:5], 0, v[2:3]
	global_load_dword v1, v[4:5], off
	v_lshl_add_u64 v[4:5], s[6:7], 0, v[2:3]
	global_load_dword v4, v[4:5], off
	v_lshl_add_u64 v[6:7], s[8:9], 0, v[2:3]
	s_waitcnt vmcnt(0)
	v_mul_f32_e32 v5, v1, v4
	s_nop 1
	v_mov_b32_dpp v5, v5 quad_perm:[1,0,3,2] row_mask:0xf bank_mask:0xf
	s_waitcnt lgkmcnt(0)
	v_fmac_f32_e32 v5, v1, v4
	s_nop 1
	v_mov_b32_dpp v1, v5 quad_perm:[2,3,0,1] row_mask:0xf bank_mask:0xf
	s_waitcnt lgkmcnt(0)
	v_add_f32_e32 v1, v5, v1
	global_load_dword v5, v[6:7], off
	v_lshl_add_u64 v[6:7], s[10:11], 0, v[2:3]
	global_load_dword v6, v[6:7], off
	s_nop 1
	v_mov_b32_dpp v4, v1 row_half_mirror row_mask:0xf bank_mask:0xf
	s_waitcnt lgkmcnt(0)
	v_add_f32_e32 v1, v1, v4
	s_nop 1
	v_mov_b32_dpp v4, v1 row_mirror row_mask:0xf bank_mask:0xf
	s_waitcnt lgkmcnt(0)
	v_add_f32_e32 v1, v1, v4
	v_mov_b32_e32 v4, v1
	s_nop 1
	v_permlane16_swap_b32_e32 v1, v4
	s_waitcnt lgkmcnt(0)
	v_add_f32_e32 v1, v1, v4
	v_mov_b32_e32 v4, v1
	s_nop 1
	v_permlane32_swap_b32_e32 v1, v4
	s_waitcnt vmcnt(0)
	v_mul_f32_e32 v7, v5, v6
	s_nop 1
	v_mov_b32_dpp v7, v7 quad_perm:[1,0,3,2] row_mask:0xf bank_mask:0xf
	s_waitcnt lgkmcnt(0)
	v_fmac_f32_e32 v7, v5, v6
	s_nop 1
	v_mov_b32_dpp v5, v7 quad_perm:[2,3,0,1] row_mask:0xf bank_mask:0xf
	s_waitcnt lgkmcnt(0)
	v_add_f32_e32 v5, v7, v5
	s_nop 1
	v_mov_b32_dpp v6, v5 row_half_mirror row_mask:0xf bank_mask:0xf
	s_waitcnt lgkmcnt(0)
	v_add_f32_e32 v5, v5, v6
	s_nop 1
	v_mov_b32_dpp v6, v5 row_mirror row_mask:0xf bank_mask:0xf
	s_waitcnt lgkmcnt(0)
	v_add_f32_e32 v5, v5, v6
	v_mov_b32_e32 v6, v5
	s_nop 1
	v_permlane16_swap_b32_e32 v5, v6
	s_waitcnt lgkmcnt(0)
	v_add_f32_e32 v5, v5, v6
	v_mov_b32_e32 v6, v5
	s_nop 1
	v_permlane32_swap_b32_e32 v5, v6
	s_and_saveexec_b64 s[6:7], vcc
	s_cbranch_execz .LBB0_296
	v_readlane_b32 s4, v255, 4
	v_add_f32_e32 v1, v1, v4
	v_mul_f32_e32 v4, 0x3fb8aa3b, v1
	v_cvt_f32_u32_e32 v7, s4
	v_readlane_b32 s5, v255, 5
	s_mov_b32 s1, 0xc2ce8ed0
	s_mov_b32 s8, 0x42b17218
	v_mul_f32_e32 v7, 0xbe99999a, v7
	v_mul_f32_e32 v8, 0x3fb8aa3b, v7
	v_fma_f32 v9, v7, s36, -v8
	v_rndne_f32_e32 v10, v8
	v_fmac_f32_e32 v9, 0x32a5705f, v7
	v_sub_f32_e32 v8, v8, v10
	v_add_f32_e32 v8, v8, v9
	v_cvt_i32_f32_e32 v10, v10
	v_exp_f32_e32 v8, v8
	v_fma_f32 v9, v1, s36, -v4
	v_fmac_f32_e32 v9, 0x32a5705f, v1
	v_cmp_ngt_f32_e64 s[4:5], s1, v7
	v_ldexp_f32 v8, v8, v10
	v_rndne_f32_e32 v10, v4
	v_sub_f32_e32 v4, v4, v10
	v_add_f32_e32 v4, v4, v9
	v_exp_f32_e32 v4, v4
	v_cvt_i32_f32_e32 v9, v10
	v_cndmask_b32_e64 v8, 0, v8, s[4:5]
	v_cmp_nlt_f32_e64 s[4:5], s8, v7
	v_mov_b32_e32 v10, 0x7f800000
	v_add_f32_e32 v5, v5, v6
	v_cndmask_b32_e64 v7, v10, v8, s[4:5]
	v_mov_b32_e32 v6, 0x3f4ccccd
	v_fmamk_f32 v6, v7, 0xbf19999a, v6
	v_mul_f32_e32 v7, 0x3fb8aa3b, v5
	v_ldexp_f32 v4, v4, v9
	v_fma_f32 v8, v5, s36, -v7
	v_rndne_f32_e32 v9, v7
	v_fmac_f32_e32 v8, 0x32a5705f, v5
	v_sub_f32_e32 v7, v7, v9
	v_add_f32_e32 v7, v7, v8
	v_exp_f32_e32 v7, v7
	v_cvt_i32_f32_e32 v8, v9
	v_cmp_ngt_f32_e64 s[4:5], s1, v1
	s_nop 1
	v_cndmask_b32_e64 v4, 0, v4, s[4:5]
	v_cmp_nlt_f32_e64 s[4:5], s8, v1
	s_nop 1
	v_cndmask_b32_e64 v1, v10, v4, s[4:5]
	v_ldexp_f32 v4, v7, v8
	v_cmp_ngt_f32_e64 s[4:5], s1, v5
	s_add_i32 s1, 0, 0x1c000
	s_nop 0
	v_cndmask_b32_e64 v4, 0, v4, s[4:5]
	v_cmp_nlt_f32_e64 s[4:5], s8, v5
	v_sub_f32_e32 v5, 1.0, v6
	s_nop 0
	v_cndmask_b32_e64 v4, v10, v4, s[4:5]
	v_sub_f32_e32 v1, v1, v4
	v_add_f32_e32 v4, v6, v1
	v_mov_b32_e32 v1, s1
	ds_write_b64 v1, v[4:5]
.LBB0_296:
	s_or_b64 exec, exec, s[6:7]
	s_load_dwordx4 s[12:15], s[2:3], 0x30
	s_load_dwordx8 s[4:11], s[2:3], 0x68
	s_mov_b32 s1, 2
	v_mov_b32_e32 v21, 0
	v_mov_b32_e32 v23, 0
	s_waitcnt lgkmcnt(0)
	v_lshl_add_u64 v[4:5], s[12:13], 0, v[2:3]
	global_load_dword v1, v[4:5], off
	v_lshl_add_u64 v[6:7], s[14:15], 0, v[2:3]
	v_lshl_add_u64 v[8:9], s[6:7], 0, v[2:3]
	v_lshl_add_u64 v[10:11], s[8:9], 0, v[2:3]
	s_load_dwordx4 s[12:15], s[2:3], 0x98
	s_waitcnt lgkmcnt(0)
	v_lshl_add_u64 v[12:13], s[12:13], 0, v[2:3]
	v_lshl_add_u64 v[2:3], s[14:15], 0, v[2:3]
	s_add_u32 s12, s10, s0
	s_addc_u32 s13, s11, 0
	s_mov_b64 s[14:15], 0
	s_waitcnt vmcnt(0)
	v_and_b32_e32 v4, 0x7fffffff, v1
	s_nop 1
	v_mov_b32_dpp v4, v4 quad_perm:[1,0,3,2] row_mask:0xf bank_mask:0xf
	v_max_f32_e64 v1, |v1|, |v1|
	s_waitcnt lgkmcnt(0)
	v_max_f32_e32 v4, v4, v4
	v_max_f32_e32 v1, v1, v4
	s_nop 1
	v_mov_b32_dpp v4, v1 quad_perm:[2,3,0,1] row_mask:0xf bank_mask:0xf
	s_waitcnt lgkmcnt(0)
	v_max_f32_e32 v4, v4, v4
	v_max_f32_e32 v1, v1, v4
	s_nop 1
	v_mov_b32_dpp v4, v1 row_half_mirror row_mask:0xf bank_mask:0xf
	s_waitcnt lgkmcnt(0)
	v_max_f32_e32 v4, v4, v4
	v_max_f32_e32 v1, v1, v4
	s_nop 1
	v_mov_b32_dpp v4, v1 row_mirror row_mask:0xf bank_mask:0xf
	s_waitcnt lgkmcnt(0)
	v_max_f32_e32 v4, v4, v4
	v_max_f32_e32 v1, v1, v4
	ds_swizzle_b32 v4, v1 offset:swizzle(SWAP,16)
	s_waitcnt lgkmcnt(0)
	v_max_f32_e32 v4, v4, v4
	v_max_f32_e32 v4, v1, v4
	global_load_dword v1, v[6:7], off
	v_mov_b32_e32 v5, v4
	s_nop 1
	v_permlane32_swap_b32_e32 v4, v5
	s_waitcnt vmcnt(0)
	v_and_b32_e32 v6, 0x7fffffff, v1
	s_nop 1
	v_mov_b32_dpp v6, v6 quad_perm:[1,0,3,2] row_mask:0xf bank_mask:0xf
	v_max_f32_e64 v1, |v1|, |v1|
	s_waitcnt lgkmcnt(0)
; __global__ void __launch_bounds__(NTHREADS, 2) hymba_fwd(Args args) {
;     ...
;                 const float gqa = wmax(ap_->in[I_QNA][l * 64 + lane]), gka = wmax(ap_->in[I_KNA][l * 64 + lane]), gqb = wmax(ap_->in[I_QNB][l * 64 + lane]), gkb = wmax(ap_->in[I_KNB][l * 64 + lane]);
;                 const float gqc = wmax(ap_->in[I_QNC][l * 64 + lane]), gkc = wmax(ap_->in[I_KNC][l * 64 + lane]);
;                 const float rbm = wmax(fmaxf(fabsf(ap_->in[I_RELB][lane]), fabsf(ap_->in[I_RELB][64 + lane])));
;                 float nb = 0.f; for (int i = lane; i < 4 * 15 * 31; i += 64) nb = fmaxf(nb, fabsf(ap_->in[I_NAB][(size_t)l * 4 * 15 * 31 + i])); nb = wmax(nb);
	v_max_f32_e32 v6, v6, v6
	v_max_f32_e32 v1, v1, v6
	s_nop 1
	v_mov_b32_dpp v6, v1 quad_perm:[2,3,0,1] row_mask:0xf bank_mask:0xf
	s_waitcnt lgkmcnt(0)
	v_max_f32_e32 v6, v6, v6
	v_max_f32_e32 v1, v1, v6
	s_nop 1
	v_mov_b32_dpp v6, v1 row_half_mirror row_mask:0xf bank_mask:0xf
	s_waitcnt lgkmcnt(0)
	v_max_f32_e32 v6, v6, v6
	v_max_f32_e32 v1, v1, v6
	s_nop 1
	v_mov_b32_dpp v6, v1 row_mirror row_mask:0xf bank_mask:0xf
	s_waitcnt lgkmcnt(0)
	v_max_f32_e32 v6, v6, v6
	v_max_f32_e32 v1, v1, v6
	ds_swizzle_b32 v6, v1 offset:swizzle(SWAP,16)
	s_waitcnt lgkmcnt(0)
	v_max_f32_e32 v6, v6, v6
	v_max_f32_e32 v6, v1, v6
	global_load_dword v1, v[8:9], off
	v_mov_b32_e32 v7, v6
	s_nop 1
	v_permlane32_swap_b32_e32 v6, v7
	s_waitcnt vmcnt(0)
	v_and_b32_e32 v8, 0x7fffffff, v1
	s_nop 1
	v_mov_b32_dpp v8, v8 quad_perm:[1,0,3,2] row_mask:0xf bank_mask:0xf
	v_max_f32_e64 v1, |v1|, |v1|
	s_waitcnt lgkmcnt(0)
	v_max_f32_e32 v8, v8, v8
	v_max_f32_e32 v1, v1, v8
	s_nop 1
	v_mov_b32_dpp v8, v1 quad_perm:[2,3,0,1] row_mask:0xf bank_mask:0xf
	s_waitcnt lgkmcnt(0)
	v_max_f32_e32 v8, v8, v8
	v_max_f32_e32 v1, v1, v8
	s_nop 1
	v_mov_b32_dpp v8, v1 row_half_mirror row_mask:0xf bank_mask:0xf
	s_waitcnt lgkmcnt(0)
	v_max_f32_e32 v8, v8, v8
	v_max_f32_e32 v1, v1, v8
	s_nop 1
	v_mov_b32_dpp v8, v1 row_mirror row_mask:0xf bank_mask:0xf
	s_waitcnt lgkmcnt(0)
	v_max_f32_e32 v8, v8, v8
	v_max_f32_e32 v1, v1, v8
	ds_swizzle_b32 v8, v1 offset:swizzle(SWAP,16)
	s_waitcnt lgkmcnt(0)
	v_max_f32_e32 v8, v8, v8
	v_max_f32_e32 v8, v1, v8
	global_load_dword v1, v[10:11], off
	v_mov_b32_e32 v9, v8
	s_nop 1
	v_permlane32_swap_b32_e32 v8, v9
	s_waitcnt vmcnt(0)
	v_and_b32_e32 v10, 0x7fffffff, v1
	s_nop 1
	v_mov_b32_dpp v10, v10 quad_perm:[1,0,3,2] row_mask:0xf bank_mask:0xf
	v_max_f32_e64 v1, |v1|, |v1|
	s_waitcnt lgkmcnt(0)
	v_max_f32_e32 v10, v10, v10
	v_max_f32_e32 v1, v1, v10
	s_nop 1
	v_mov_b32_dpp v10, v1 quad_perm:[2,3,0,1] row_mask:0xf bank_mask:0xf
	s_waitcnt lgkmcnt(0)
	v_max_f32_e32 v10, v10, v10
	v_max_f32_e32 v1, v1, v10
	s_nop 1
	v_mov_b32_dpp v10, v1 row_half_mirror row_mask:0xf bank_mask:0xf
	s_waitcnt lgkmcnt(0)
	v_max_f32_e32 v10, v10, v10
	v_max_f32_e32 v1, v1, v10
	s_nop 1
	v_mov_b32_dpp v10, v1 row_mirror row_mask:0xf bank_mask:0xf
	s_waitcnt lgkmcnt(0)
	v_max_f32_e32 v10, v10, v10
	v_max_f32_e32 v1, v1, v10
	ds_swizzle_b32 v10, v1 offset:swizzle(SWAP,16)
	s_waitcnt lgkmcnt(0)
	v_max_f32_e32 v10, v10, v10
	v_max_f32_e32 v10, v1, v10
	global_load_dword v1, v[12:13], off
	v_mov_b32_e32 v11, v10
	s_nop 1
	v_permlane32_swap_b32_e32 v10, v11
	s_waitcnt vmcnt(0)
	v_and_b32_e32 v12, 0x7fffffff, v1
	s_nop 1
	v_mov_b32_dpp v12, v12 quad_perm:[1,0,3,2] row_mask:0xf bank_mask:0xf
	v_max_f32_e64 v1, |v1|, |v1|
	s_waitcnt lgkmcnt(0)
	v_max_f32_e32 v12, v12, v12
	v_max_f32_e32 v1, v1, v12
	s_nop 1
	v_mov_b32_dpp v12, v1 quad_perm:[2,3,0,1] row_mask:0xf bank_mask:0xf
	s_waitcnt lgkmcnt(0)
	v_max_f32_e32 v12, v12, v12
	v_max_f32_e32 v1, v1, v12
	s_nop 1
	v_mov_b32_dpp v12, v1 row_half_mirror row_mask:0xf bank_mask:0xf
	s_waitcnt lgkmcnt(0)
	v_max_f32_e32 v12, v12, v12
	v_max_f32_e32 v1, v1, v12
	s_nop 1
	v_mov_b32_dpp v12, v1 row_mirror row_mask:0xf bank_mask:0xf
	s_waitcnt lgkmcnt(0)
	v_max_f32_e32 v12, v12, v12
	v_max_f32_e32 v1, v1, v12
	ds_swizzle_b32 v12, v1 offset:swizzle(SWAP,16)
	s_waitcnt lgkmcnt(0)
	v_max_f32_e32 v12, v12, v12
	v_max_f32_e32 v12, v1, v12
	global_load_dword v1, v[2:3], off
	v_mov_b32_e32 v13, v12
	s_nop 1
	v_permlane32_swap_b32_e32 v12, v13
	s_waitcnt vmcnt(0)
	v_and_b32_e32 v2, 0x7fffffff, v1
	s_nop 1
	v_mov_b32_dpp v2, v2 quad_perm:[1,0,3,2] row_mask:0xf bank_mask:0xf
	v_max_f32_e64 v1, |v1|, |v1|
	s_waitcnt lgkmcnt(0)
	v_max_f32_e32 v2, v2, v2
	v_max_f32_e32 v1, v1, v2
	s_nop 1
	v_mov_b32_dpp v2, v1 quad_perm:[2,3,0,1] row_mask:0xf bank_mask:0xf
	s_waitcnt lgkmcnt(0)
	v_max_f32_e32 v2, v2, v2
	v_max_f32_e32 v1, v1, v2
	s_nop 1
	v_mov_b32_dpp v2, v1 row_half_mirror row_mask:0xf bank_mask:0xf
	s_waitcnt lgkmcnt(0)
	v_max_f32_e32 v2, v2, v2
	v_max_f32_e32 v1, v1, v2
	s_nop 1
	v_mov_b32_dpp v2, v1 row_mirror row_mask:0xf bank_mask:0xf
	s_waitcnt lgkmcnt(0)
	v_max_f32_e32 v2, v2, v2
	v_max_f32_e32 v1, v1, v2
	ds_swizzle_b32 v2, v1 offset:swizzle(SWAP,16)
	s_waitcnt lgkmcnt(0)
	v_max_f32_e32 v2, v2, v2
	v_max_f32_e32 v14, v1, v2
	v_lshlrev_b32_e32 v1, 2, v0
	global_load_dword v2, v1, s[4:5]
	s_nop 0
	global_load_dword v1, v1, s[4:5] offset:256
	v_mov_b32_e32 v15, v14
	s_nop 1
	v_permlane32_swap_b32_e32 v14, v15
	s_waitcnt vmcnt(1)
	v_max_f32_e64 v2, |v2|, |v2|
	s_waitcnt vmcnt(0)
	v_max_f32_e64 v1, |v1|, |v1|
	v_max_f32_e32 v1, v2, v1
	s_nop 1
	v_mov_b32_dpp v2, v1 quad_perm:[1,0,3,2] row_mask:0xf bank_mask:0xf
	s_waitcnt lgkmcnt(0)
	v_max_f32_e32 v2, v2, v2
	v_max_f32_e32 v1, v1, v2
	s_nop 1
	v_mov_b32_dpp v2, v1 quad_perm:[2,3,0,1] row_mask:0xf bank_mask:0xf
	s_waitcnt lgkmcnt(0)
	v_max_f32_e32 v2, v2, v2
	v_max_f32_e32 v1, v1, v2
	s_nop 1
	v_mov_b32_dpp v2, v1 row_half_mirror row_mask:0xf bank_mask:0xf
	s_waitcnt lgkmcnt(0)
	v_max_f32_e32 v2, v2, v2
	v_max_f32_e32 v1, v1, v2
	s_nop 1
	v_mov_b32_dpp v2, v1 row_mirror row_mask:0xf bank_mask:0xf
	s_waitcnt lgkmcnt(0)
	v_max_f32_e32 v2, v2, v2
	v_max_f32_e32 v1, v1, v2
	ds_swizzle_b32 v2, v1 offset:swizzle(SWAP,16)
	s_waitcnt lgkmcnt(0)
	v_max_f32_e32 v2, v2, v2
	v_max_f32_e32 v16, v1, v2
	v_sub_u32_e32 v1, 0x743, v0
	v_lshrrev_b32_e32 v1, 6, v1
	v_mov_b32_e32 v17, v16
	v_add_u32_e32 v19, 1, v1
	v_or_b32_e32 v1, 64, v0
	v_permlane32_swap_b32_e32 v16, v17
	v_and_b32_e32 v18, 30, v19
	v_mov_b64_e32 v[2:3], v[0:1]

; __global__ void __launch_bounds__(NTHREADS, 2) hymba_fwd(Args args) {
;     ...
;                 float nb = 0.f; for (int i = lane; i < 4 * 15 * 31; i += 64) nb = fmaxf(nb, fabsf(ap_->in[I_NAB][(size_t)l * 4 * 15 * 31 + i])); nb = wmax(nb);
;                 if (lane == 0) { misc[2] = 1.02f * 64.f * C2 * gqa * gka + rbm * LOG2E; misc[3] = 1.02f * 64.f * C2 * gqb * gkb + nb * LOG2E; misc[4] = 1.02f * 64.f * C2 * gqc * gkc; } }
.LBB0_302:
	s_or_b64 exec, exec, s[6:7]
	v_and_b32_e32 v0, 0x7fffffff, v2
	s_nop 1
	v_mov_b32_dpp v0, v0 quad_perm:[1,0,3,2] row_mask:0xf bank_mask:0xf
	v_max_f32_e64 v1, |v2|, |v2|
	s_waitcnt lgkmcnt(0)
	v_max_f32_e32 v0, v0, v0
	v_max_f32_e32 v0, v1, v0
	s_nop 1
	v_mov_b32_dpp v1, v0 quad_perm:[2,3,0,1] row_mask:0xf bank_mask:0xf
	s_waitcnt lgkmcnt(0)
	v_max_f32_e32 v1, v1, v1
	v_max_f32_e32 v0, v0, v1
	s_nop 1
	v_mov_b32_dpp v1, v0 row_half_mirror row_mask:0xf bank_mask:0xf
	s_waitcnt lgkmcnt(0)
	v_max_f32_e32 v1, v1, v1
	v_max_f32_e32 v0, v0, v1
	s_nop 1
	v_mov_b32_dpp v1, v0 row_mirror row_mask:0xf bank_mask:0xf
	s_waitcnt lgkmcnt(0)
	v_max_f32_e32 v1, v1, v1
	v_max_f32_e32 v0, v0, v1
	ds_swizzle_b32 v1, v0 offset:swizzle(SWAP,16)
	s_waitcnt lgkmcnt(0)
	v_max_f32_e32 v1, v1, v1
	v_max_f32_e32 v0, v0, v1
	v_mov_b32_e32 v1, v0
	s_nop 1
	v_permlane32_swap_b32_e32 v0, v1
	s_and_saveexec_b64 s[4:5], vcc
	s_cbranch_execz .LBB0_304
	v_max_f32_e32 v2, v16, v16
	v_max_f32_e32 v3, v17, v17
	v_max_f32_e32 v12, v12, v12
	v_max_f32_e32 v13, v13, v13
	v_max_f32_e32 v2, v2, v3
	v_max_f32_e32 v3, v14, v14
	v_max_f32_e32 v14, v15, v15
	v_max_f32_e32 v12, v12, v13
	v_max_f32_e32 v8, v8, v8
	v_max_f32_e32 v9, v9, v9
	v_max_f32_e32 v4, v4, v4
	v_max_f32_e32 v5, v5, v5
	v_max_f32_e32 v3, v3, v14
	v_max_f32_e32 v9, v8, v9
	v_max_f32_e32 v8, v4, v5
	v_mul_f32_e32 v4, 0x413c5bb7, v12
	v_max_f32_e32 v0, v0, v0
	v_max_f32_e32 v1, v1, v1
	v_max_f32_e32 v10, v10, v10
	v_max_f32_e32 v11, v11, v11
	v_max_f32_e32 v6, v6, v6
	v_max_f32_e32 v7, v7, v7
	v_mul_f32_e32 v4, v4, v3
	v_max_f32_e32 v3, v0, v1
	s_mov_b32 s0, 0x413c5bb7
	v_max_f32_e32 v11, v10, v11
	v_max_f32_e32 v10, v6, v7
	v_pk_mul_f32 v[0:1], v[8:9], s[0:1] op_sel_hi:[1,0]
	v_pk_mul_f32 v[2:3], v[2:3], s[36:37] op_sel_hi:[1,0]
	v_readlane_b32 s0, v254, 50
	v_pk_fma_f32 v[0:1], v[0:1], v[10:11], v[2:3]
	s_nop 0
	v_mov_b32_e32 v2, s0
	v_readlane_b32 s0, v254, 51
	ds_write_b64 v2, v[0:1]
	s_nop 0
	v_mov_b32_e32 v0, s0
	ds_write_b32 v0, v4

; __device__ __forceinline__ int crow(int r, int hi) { return (r & 3) + 8 * (r >> 2) + 4 * hi; }
; template <int MODE>
; __device__ __forceinline__ void attn_unit(const UnitArgs& A, char* lds, const int wave_) {
;     ...
;         __syncthreads();
;         if (half == 0) {
;             float ssq[16];
; #pragma unroll
;             for (int r = 0; r < 16; ++r) { float s = 0.f;
; #pragma unroll
;                 for (int d0 = 0; d0 < 4; ++d0) { const float v = o[d0][r] * rli[r] - pb[crow(r, hi) * 128 + d0 * 32 + r32]; o[d0][r] = v; s += v * v; }
;                 ssq[r] = s; }
; #pragma unroll
;             for (int r = 0; r < 16; ++r) { float v = ssq[r]; v = bfly_add<1>(v); v = bfly_add<2>(v); v = bfly_add<4>(v); v = bfly_add<8>(v); v = bfly_add<16>(v); ssq[r] = v; }
;             float gv[4];
; #pragma unroll
;             for (int d0 = 0; d0 < 4; ++d0) gv[d0] = A.subg[d0 * 32 + r32] * A.oscale;
.LBB0_343:
	s_cmpk_gt_u32 s0, 0xff
	s_waitcnt lgkmcnt(0)
	s_barrier
	s_cbranch_scc1 .LBB0_307
	ds_read2_b32 v[94:95], v77 offset0:128 offset1:160
	ds_read2_b32 v[90:91], v77 offset1:32
	v_mov_b32_e32 v92, v0
	v_mov_b32_e32 v93, v16
	v_mov_b32_e32 v16, v1
	ds_read2_b32 v[0:1], v77 offset0:192 offset1:224
	v_add_u32_e32 v65, 0x400, v77
	s_waitcnt lgkmcnt(2)
	v_pk_fma_f32 v[118:119], v[16:17], v[84:85], v[94:95] op_sel_hi:[1,0,1] neg_lo:[0,0,1] neg_hi:[0,0,1]
	ds_read2_b32 v[16:17], v65 offset1:32
	s_waitcnt lgkmcnt(2)
	v_pk_fma_f32 v[128:129], v[92:93], v[86:87], v[90:91] op_sel_hi:[1,0,1] neg_lo:[0,0,1] neg_hi:[0,0,1]
	v_mov_b32_e32 v93, v48
	v_mov_b32_e32 v48, v33
	s_waitcnt lgkmcnt(1)
	v_pk_fma_f32 v[114:115], v[48:49], v[84:85], v[0:1] op_sel_hi:[1,0,1] neg_lo:[0,0,1] neg_hi:[0,0,1]
	v_mov_b32_e32 v0, v2
	v_mov_b32_e32 v1, v18
	v_mov_b32_e32 v92, v32
	s_waitcnt lgkmcnt(0)
	v_pk_fma_f32 v[110:111], v[0:1], v[82:83], v[16:17] op_sel_hi:[1,0,1] neg_lo:[0,0,1] neg_hi:[0,0,1]
	ds_read2_b32 v[0:1], v65 offset0:64 offset1:96
	ds_read2_b32 v[32:33], v65 offset0:128 offset1:160
	v_mov_b32_e32 v16, v34
	v_mov_b32_e32 v17, v50
	v_mov_b32_e32 v18, v3
	ds_read2_b32 v[90:91], v77 offset0:64 offset1:96
	s_waitcnt lgkmcnt(2)
	v_pk_fma_f32 v[112:113], v[16:17], v[82:83], v[0:1] op_sel_hi:[1,0,1] neg_lo:[0,0,1] neg_hi:[0,0,1]
	s_waitcnt lgkmcnt(1)
	v_pk_fma_f32 v[96:97], v[18:19], v[78:79], v[32:33] op_sel_hi:[1,0,1] neg_lo:[0,0,1] neg_hi:[0,0,1]
	ds_read2_b32 v[0:1], v65 offset0:192 offset1:224
	v_add_u32_e32 v18, 0x1000, v77
	ds_read2_b32 v[2:3], v18 offset1:32
	v_mov_b32_e32 v50, v35
	s_waitcnt lgkmcnt(2)
	v_pk_fma_f32 v[130:131], v[92:93], v[86:87], v[90:91] op_sel_hi:[1,0,1] neg_lo:[0,0,1] neg_hi:[0,0,1]
	s_waitcnt lgkmcnt(1)
	v_pk_fma_f32 v[90:91], v[50:51], v[78:79], v[0:1] op_sel_hi:[1,0,1] neg_lo:[0,0,1] neg_hi:[0,0,1]
	v_mov_b32_e32 v0, v4
	v_mov_b32_e32 v1, v20
	s_waitcnt lgkmcnt(0)
	v_pk_fma_f32 v[82:83], v[0:1], v[68:69], v[2:3] op_sel_hi:[1,0,1] neg_lo:[0,0,1] neg_hi:[0,0,1]
	ds_read2_b32 v[0:1], v18 offset0:64 offset1:96
	ds_read2_b32 v[16:17], v18 offset0:128 offset1:160
	v_mov_b32_e32 v2, v36
	v_mov_b32_e32 v3, v52
	v_mov_b32_e32 v20, v5
	s_waitcnt lgkmcnt(1)
	v_pk_fma_f32 v[84:85], v[2:3], v[68:69], v[0:1] op_sel_hi:[1,0,1] neg_lo:[0,0,1] neg_hi:[0,0,1]
	s_waitcnt lgkmcnt(0)
	v_pk_fma_f32 v[68:69], v[20:21], v[66:67], v[16:17] op_sel_hi:[1,0,1] neg_lo:[0,0,1] neg_hi:[0,0,1]
	ds_read2_b32 v[0:1], v18 offset0:192 offset1:224
	v_add_u32_e32 v16, 0x1400, v77
	ds_read2_b32 v[2:3], v16 offset1:32
	v_mov_b32_e32 v52, v37
	ds_read2_b32 v[4:5], v16 offset0:128 offset1:160
	s_waitcnt lgkmcnt(2)
	v_pk_fma_f32 v[66:67], v[52:53], v[66:67], v[0:1] op_sel_hi:[1,0,1] neg_lo:[0,0,1] neg_hi:[0,0,1]
	v_mov_b32_e32 v0, v6
	v_mov_b32_e32 v1, v22
	s_waitcnt lgkmcnt(1)
	v_pk_fma_f32 v[52:53], v[0:1], v[64:65], v[2:3] op_sel_hi:[1,0,1] neg_lo:[0,0,1] neg_hi:[0,0,1]
	ds_read2_b32 v[0:1], v16 offset0:64 offset1:96
	v_mov_b32_e32 v2, v38
	v_mov_b32_e32 v3, v54
	v_add_u32_e32 v6, 0x2000, v77
	v_mov_b32_e32 v54, v39
	s_waitcnt lgkmcnt(0)
	v_pk_fma_f32 v[64:65], v[2:3], v[64:65], v[0:1] op_sel_hi:[1,0,1] neg_lo:[0,0,1] neg_hi:[0,0,1]
	ds_read2_b32 v[0:1], v16 offset0:192 offset1:224
	ds_read2_b32 v[2:3], v6 offset1:32
	v_mov_b32_e32 v22, v7
	v_pk_fma_f32 v[48:49], v[22:23], v[72:73], v[4:5] op_sel_hi:[1,0,1] neg_lo:[0,0,1] neg_hi:[0,0,1]
	ds_read2_b32 v[4:5], v6 offset0:128 offset1:160
	s_waitcnt lgkmcnt(2)
	v_pk_fma_f32 v[38:39], v[54:55], v[72:73], v[0:1] op_sel_hi:[1,0,1] neg_lo:[0,0,1] neg_hi:[0,0,1]
	v_mov_b32_e32 v0, v8
	v_mov_b32_e32 v1, v24
	s_waitcnt lgkmcnt(1)
	v_pk_fma_f32 v[32:33], v[0:1], v[74:75], v[2:3] op_sel_hi:[1,0,1] neg_lo:[0,0,1] neg_hi:[0,0,1]
	ds_read2_b32 v[0:1], v6 offset0:64 offset1:96
	v_mov_b32_e32 v2, v40
	v_mov_b32_e32 v3, v56
	v_mov_b32_e32 v24, v9
	v_mov_b32_e32 v56, v41
	s_waitcnt lgkmcnt(0)
	v_pk_fma_f32 v[34:35], v[2:3], v[74:75], v[0:1] op_sel_hi:[1,0,1] neg_lo:[0,0,1] neg_hi:[0,0,1]
	ds_read2_b32 v[0:1], v6 offset0:192 offset1:224
	v_add_u32_e32 v6, 0x2400, v77
	v_pk_fma_f32 v[16:17], v[24:25], v[70:71], v[4:5] op_sel_hi:[1,0,1] neg_lo:[0,0,1] neg_hi:[0,0,1]
	global_load_dword v99, v81, s[4:5]
	v_mov_b32_e32 v2, v10
	s_waitcnt lgkmcnt(0)
	v_pk_fma_f32 v[70:71], v[56:57], v[70:71], v[0:1] op_sel_hi:[1,0,1] neg_lo:[0,0,1] neg_hi:[0,0,1]
	ds_read2_b32 v[0:1], v6 offset1:32
	global_load_dword v103, v81, s[4:5] offset:128
	global_load_dword v105, v81, s[4:5] offset:256
	global_load_dword v144, v81, s[4:5] offset:384
	v_mov_b32_e32 v3, v26
	ds_read2_b32 v[4:5], v6 offset0:128 offset1:160
	v_mov_b32_e32 v26, v11
	s_waitcnt lgkmcnt(1)
	v_pk_fma_f32 v[56:57], v[2:3], v[88:89], v[0:1] op_sel_hi:[1,0,1] neg_lo:[0,0,1] neg_hi:[0,0,1]
	ds_read2_b32 v[0:1], v6 offset0:64 offset1:96
	v_mov_b32_e32 v2, v42
	v_mov_b32_e32 v3, v58
	v_mov_b32_e32 v58, v43
	v_pk_mul_f32 v[140:141], v[128:129], v[128:129]
	s_waitcnt lgkmcnt(0)
; __device__ __forceinline__ int crow(int r, int hi) { return (r & 3) + 8 * (r >> 2) + 4 * hi; }
; template <int MODE>
; __device__ __forceinline__ void attn_unit(const UnitArgs& A, char* lds, const int wave_) {
;     ...
;             for (int r = 0; r < 16; ++r) { float s = 0.f;
; #pragma unroll
;                 for (int d0 = 0; d0 < 4; ++d0) { const float v = o[d0][r] * rli[r] - pb[crow(r, hi) * 128 + d0 * 32 + r32]; o[d0][r] = v; s += v * v; }
;                 ssq[r] = s; }
; #pragma unroll
;             for (int r = 0; r < 16; ++r) { float v = ssq[r]; v = bfly_add<1>(v); v = bfly_add<2>(v); v = bfly_add<4>(v); v = bfly_add<8>(v); v = bfly_add<16>(v); ssq[r] = v; }
	v_pk_fma_f32 v[54:55], v[2:3], v[88:89], v[0:1] op_sel_hi:[1,0,1] neg_lo:[0,0,1] neg_hi:[0,0,1]
	ds_read2_b32 v[0:1], v6 offset0:192 offset1:224
	v_add_u32_e32 v6, 0x3000, v77
	ds_read2_b32 v[2:3], v6 offset1:32
	v_add_u32_e32 v77, 0x3400, v77
	v_pk_mul_f32 v[152:153], v[118:119], v[118:119]
	v_pk_mul_f32 v[142:143], v[130:131], v[130:131]
	v_pk_mul_f32 v[154:155], v[114:115], v[114:115]
	v_mov_b32_e32 v10, v152
	v_mov_b32_e32 v11, v140
	v_mov_b32_e32 v140, v153
	v_pk_add_f32 v[10:11], v[10:11], v[140:141]
	v_mov_b32_e32 v22, v154
	v_mov_b32_e32 v23, v142
	v_pk_add_f32 v[10:11], v[10:11], v[22:23]
	v_mov_b32_e32 v142, v155
	v_mov_b32_e32 v7, v62
	v_mov_b32_e32 v62, v47
	s_lshl_b64 s[6:7], s[84:85], 11
	s_add_u32 s0, s39, s6
	s_addc_u32 s6, s40, s7
	s_add_u32 s0, s0, s2
	s_addc_u32 s2, s6, s3
	s_lshl_b32 s1, s1, 16
	s_add_u32 s0, s0, s1
	s_addc_u32 s1, s2, 0
	s_brev_b32 s2, 60
	v_pk_mul_f32 v[132:133], v[110:111], v[110:111]
	v_pk_mul_f32 v[136:137], v[96:97], v[96:97]
	v_pk_mul_f32 v[134:135], v[112:113], v[112:113]
	v_pk_mul_f32 v[138:139], v[90:91], v[90:91]
	v_pk_mul_f32 v[116:117], v[82:83], v[82:83]
	v_pk_mul_f32 v[122:123], v[68:69], v[68:69]
	v_pk_mul_f32 v[120:121], v[84:85], v[84:85]
	v_pk_mul_f32 v[124:125], v[66:67], v[66:67]
	v_pk_mul_f32 v[86:87], v[52:53], v[52:53]
	v_pk_mul_f32 v[106:107], v[48:49], v[48:49]
	v_pk_mul_f32 v[94:95], v[64:65], v[64:65]
	v_pk_mul_f32 v[108:109], v[38:39], v[38:39]
	v_pk_mul_f32 v[72:73], v[32:33], v[32:33]
	v_pk_mul_f32 v[78:79], v[16:17], v[16:17]
	v_pk_mul_f32 v[74:75], v[34:35], v[34:35]
	v_pk_mul_f32 v[126:127], v[70:71], v[70:71]
	v_pk_mul_f32 v[92:93], v[56:57], v[56:57]
	v_pk_mul_f32 v[88:89], v[54:55], v[54:55]
	s_waitcnt vmcnt(1) lgkmcnt(1)
	v_pk_fma_f32 v[24:25], v[58:59], v[104:105], v[0:1] op_sel_hi:[1,0,1] neg_lo:[0,0,1] neg_hi:[0,0,1]
	v_mov_b32_e32 v0, v12
	v_mov_b32_e32 v1, v28
	s_waitcnt lgkmcnt(0)
	v_pk_fma_f32 v[20:21], v[0:1], v[102:103], v[2:3] op_sel_hi:[1,0,1] neg_lo:[0,0,1] neg_hi:[0,0,1]
	ds_read2_b32 v[0:1], v6 offset0:64 offset1:96
	v_pk_fma_f32 v[36:37], v[26:27], v[104:105], v[4:5] op_sel_hi:[1,0,1] neg_lo:[0,0,1] neg_hi:[0,0,1]
	ds_read2_b32 v[4:5], v6 offset0:128 offset1:160
	v_mov_b32_e32 v2, v44
	v_mov_b32_e32 v3, v60
	s_waitcnt lgkmcnt(1)
	v_pk_fma_f32 v[18:19], v[2:3], v[102:103], v[0:1] op_sel_hi:[1,0,1] neg_lo:[0,0,1] neg_hi:[0,0,1]
	v_mov_b32_e32 v28, v13
	ds_read2_b32 v[0:1], v6 offset0:192 offset1:224
	s_waitcnt lgkmcnt(1)
	v_pk_fma_f32 v[8:9], v[28:29], v[98:99], v[4:5] op_sel_hi:[1,0,1] neg_lo:[0,0,1] neg_hi:[0,0,1]
	ds_read2_b32 v[4:5], v77 offset1:32
	v_mov_b32_e32 v60, v45
	v_pk_add_f32 v[26:27], v[10:11], v[142:143]
	s_waitcnt lgkmcnt(1)
	v_pk_fma_f32 v[2:3], v[60:61], v[98:99], v[0:1] op_sel_hi:[1,0,1] neg_lo:[0,0,1] neg_hi:[0,0,1]
	v_mov_b32_e32 v0, v14
	v_mov_b32_e32 v1, v30
	s_waitcnt lgkmcnt(0)
	v_pk_fma_f32 v[0:1], v[0:1], v[80:81], v[4:5] op_sel_hi:[1,0,1] neg_lo:[0,0,1] neg_hi:[0,0,1]
	ds_read2_b32 v[4:5], v77 offset0:64 offset1:96
	s_nop 1
	v_mov_b32_dpp v29, v27 quad_perm:[1,0,3,2] row_mask:0xf bank_mask:0xf
	s_nop 1
	v_mov_b32_dpp v28, v26 quad_perm:[1,0,3,2] row_mask:0xf bank_mask:0xf
	v_mov_b32_e32 v6, v46
	v_mov_b32_e32 v30, v15
	s_waitcnt lgkmcnt(0)
	v_pk_fma_f32 v[10:11], v[6:7], v[80:81], v[4:5] op_sel_hi:[1,0,1] neg_lo:[0,0,1] neg_hi:[0,0,1]
	ds_read2_b32 v[4:5], v77 offset0:128 offset1:160
	s_waitcnt lgkmcnt(0)
	v_pk_add_f32 v[6:7], v[26:27], v[28:29]
	s_nop 1
	v_mov_b32_dpp v29, v7 quad_perm:[2,3,0,1] row_mask:0xf bank_mask:0xf
	s_nop 1
	v_mov_b32_dpp v28, v6 quad_perm:[2,3,0,1] row_mask:0xf bank_mask:0xf
	ds_read2_b32 v[14:15], v77 offset0:192 offset1:224
	s_waitcnt lgkmcnt(0)
	v_pk_fma_f32 v[4:5], v[30:31], v[76:77], v[4:5] op_sel_hi:[1,0,1] neg_lo:[0,0,1] neg_hi:[0,0,1]
	s_waitcnt vmcnt(0)
	v_mul_f32_e32 v46, s12, v144
	v_lshlrev_b32_e32 v144, 1, v156
	s_waitcnt lgkmcnt(0)
	v_pk_add_f32 v[30:31], v[6:7], v[28:29]
	s_nop 1
	v_mov_b32_dpp v81, v31 row_half_mirror row_mask:0xf bank_mask:0xf
	s_nop 1
	v_mov_b32_dpp v80, v30 row_half_mirror row_mask:0xf bank_mask:0xf
	s_waitcnt lgkmcnt(0)
	v_pk_fma_f32 v[6:7], v[62:63], v[76:77], v[14:15] op_sel_hi:[1,0,1] neg_lo:[0,0,1] neg_hi:[0,0,1]
	v_lshlrev_b32_e32 v62, 13, v157
	v_mov_b32_e32 v63, v145
	v_mul_f32_e32 v60, s12, v99
	s_waitcnt lgkmcnt(0)
	v_pk_add_f32 v[14:15], v[30:31], v[80:81]
	s_nop 1
	v_mov_b32_dpp v31, v15 row_mirror row_mask:0xf bank_mask:0xf
	s_nop 1
	v_mov_b32_dpp v30, v14 row_mirror row_mask:0xf bank_mask:0xf
	v_mul_f32_e32 v61, s12, v103
	v_mul_f32_e32 v47, s12, v105
	v_mov_b32_e32 v80, v138
	v_mov_b32_e32 v81, v134
	s_waitcnt lgkmcnt(0)
	v_pk_add_f32 v[14:15], v[14:15], v[30:31]
	v_mov_b32_e32 v31, v15
	s_nop 1
	v_permlane16_swap_b32_e32 v15, v31
	v_mov_b32_e32 v30, v14
	s_nop 1
	v_permlane16_swap_b32_e32 v14, v30
	v_mov_b32_e32 v134, v139
	v_pk_mul_f32 v[100:101], v[36:37], v[36:37]
	v_pk_mul_f32 v[58:59], v[24:25], v[24:25]
	v_pk_mul_f32 v[42:43], v[20:21], v[20:21]
	s_waitcnt lgkmcnt(0)
; __device__ __forceinline__ int crow(int r, int hi) { return (r & 3) + 8 * (r >> 2) + 4 * hi; }
; template <int MODE>
; __device__ __forceinline__ void attn_unit(const UnitArgs& A, char* lds, const int wave_) {
;     ...
;             for (int r = 0; r < 16; ++r) { float v = ssq[r]; v = bfly_add<1>(v); v = bfly_add<2>(v); v = bfly_add<4>(v); v = bfly_add<8>(v); v = bfly_add<16>(v); ssq[r] = v; }
;             float gv[4];
; #pragma unroll
;             for (int d0 = 0; d0 < 4; ++d0) gv[d0] = A.subg[d0 * 32 + r32] * A.oscale;
;             __hip_bfloat16* Ow = (__hip_bfloat16*)A.Ob + (long)(qb * QBLK) * DM;
; #pragma unroll
;             for (int r = 0; r < 16; ++r) { const float rn = rsqrtf(ssq[r] * (1.f / 128.f) + EPS); const int orow = crow(r, hi);
; #pragma unroll
;                 for (int d0 = 0; d0 < 4; ++d0) Ow[(long)orow * DM + d0 * 32 + r32] = __float2bfloat16(o[d0][r] * rn * gv[d0]); }
	v_pk_add_f32 v[30:31], v[14:15], v[30:31]
	v_mov_b64_e32 v[14:15], s[78:79]
	v_pk_fma_f32 v[76:77], v[30:31], s[2:3], v[14:15] op_sel_hi:[1,0,0]
	v_pk_mul_f32 v[50:51], v[8:9], v[8:9]
	v_mul_f32_e32 v30, 0x4b800000, v77
	v_cmp_gt_f32_e32 vcc, s62, v77
	v_pk_mul_f32 v[40:41], v[18:19], v[18:19]
	v_pk_mul_f32 v[44:45], v[2:3], v[2:3]
	v_cndmask_b32_e32 v30, v77, v30, vcc
	v_rsq_f32_e32 v77, v30
	v_lshl_add_u64 v[30:31], s[0:1], 0, v[144:145]
	v_lshl_add_u64 v[30:31], v[30:31], 0, v[62:63]
	v_pk_mul_f32 v[12:13], v[0:1], v[0:1]
	v_mul_f32_e32 v62, 0x45800000, v77
	v_cndmask_b32_e32 v62, v77, v62, vcc
	v_mul_f32_e32 v63, v128, v62
	v_mul_f32_e32 v63, v63, v60
	v_cvt_pk_bf16_f32 v63, v63, s0
	global_store_short v[30:31], v63, off
	v_mul_f32_e32 v63, v129, v62
	v_mul_f32_e32 v63, v63, v61
	v_cvt_pk_bf16_f32 v63, v63, s0
	global_store_short v[30:31], v63, off offset:64
	v_mul_f32_e32 v63, v130, v62
	v_mul_f32_e32 v63, v63, v47
	v_mul_f32_e32 v62, v131, v62
	v_cvt_pk_bf16_f32 v63, v63, s0
	v_mul_f32_e32 v62, v62, v46
	global_store_short v[30:31], v63, off offset:128
	v_cvt_pk_bf16_f32 v98, v62, s0
	v_mov_b32_e32 v62, v136
	v_mov_b32_e32 v63, v132
	v_mov_b32_e32 v132, v137
	v_pk_add_f32 v[62:63], v[62:63], v[132:133]
	v_mul_f32_e32 v77, 0x4b800000, v76
	v_pk_add_f32 v[62:63], v[62:63], v[80:81]
	v_cmp_gt_f32_e32 vcc, s62, v76
	v_pk_add_f32 v[62:63], v[62:63], v[134:135]
	s_nop 1
	v_mov_b32_dpp v81, v63 quad_perm:[1,0,3,2] row_mask:0xf bank_mask:0xf
	s_nop 1
	v_mov_b32_dpp v80, v62 quad_perm:[1,0,3,2] row_mask:0xf bank_mask:0xf
	v_cndmask_b32_e32 v76, v76, v77, vcc
	v_rsq_f32_e32 v99, v76
	global_store_short v[30:31], v98, off offset:192
	v_mov_b32_e32 v98, v124
	s_waitcnt lgkmcnt(0)
	v_pk_add_f32 v[62:63], v[62:63], v[80:81]
	s_nop 1
	v_mov_b32_dpp v77, v63 quad_perm:[2,3,0,1] row_mask:0xf bank_mask:0xf
	s_nop 1
	v_mov_b32_dpp v76, v62 quad_perm:[2,3,0,1] row_mask:0xf bank_mask:0xf
	v_mul_f32_e32 v80, 0x45800000, v99
	v_cndmask_b32_e32 v80, v99, v80, vcc
	v_mul_f32_e32 v81, v118, v80
	v_mul_f32_e32 v81, v81, v60
	s_waitcnt lgkmcnt(0)
	v_pk_add_f32 v[62:63], v[62:63], v[76:77]
	s_nop 1
	v_mov_b32_dpp v77, v63 row_half_mirror row_mask:0xf bank_mask:0xf
	s_nop 1
	v_mov_b32_dpp v76, v62 row_half_mirror row_mask:0xf bank_mask:0xf
	v_cvt_pk_bf16_f32 v81, v81, s0
	global_store_short v[30:31], v81, off offset:2048
	v_mul_f32_e32 v81, v119, v80
	v_mul_f32_e32 v81, v81, v61
	s_waitcnt lgkmcnt(0)
	v_pk_add_f32 v[62:63], v[62:63], v[76:77]
	s_nop 1
	v_mov_b32_dpp v77, v63 row_mirror row_mask:0xf bank_mask:0xf
	s_nop 1
	v_mov_b32_dpp v76, v62 row_mirror row_mask:0xf bank_mask:0xf
	v_cvt_pk_bf16_f32 v81, v81, s0
	global_store_short v[30:31], v81, off offset:2112
	v_mul_f32_e32 v81, v114, v80
	v_mul_f32_e32 v80, v115, v80
	s_waitcnt lgkmcnt(0)
	v_pk_add_f32 v[62:63], v[62:63], v[76:77]
	v_mov_b32_e32 v77, v63
	s_nop 1
	v_permlane16_swap_b32_e32 v63, v77
	v_mov_b32_e32 v76, v62
	s_nop 1
	v_permlane16_swap_b32_e32 v62, v76
	v_mul_f32_e32 v81, v81, v47
	v_cvt_pk_bf16_f32 v81, v81, s0
	global_store_short v[30:31], v81, off offset:2176
	v_mov_b32_e32 v81, v116
	s_waitcnt lgkmcnt(0)
	v_pk_add_f32 v[62:63], v[62:63], v[76:77]
	v_mov_b32_e32 v116, v123
	v_pk_fma_f32 v[62:63], v[62:63], s[2:3], v[14:15] op_sel_hi:[1,0,0]
	v_mov_b32_e32 v99, v120
	v_mul_f32_e32 v76, 0x4b800000, v63
	v_cmp_gt_f32_e32 vcc, s62, v63
	v_mov_b32_e32 v120, v125
	v_pk_mul_f32 v[26:27], v[4:5], v[4:5]
	v_cndmask_b32_e32 v63, v63, v76, vcc
	v_rsq_f32_e32 v63, v63
	v_mul_f32_e32 v76, v80, v46
	v_cvt_pk_bf16_f32 v76, v76, s0
	global_store_short v[30:31], v76, off offset:2240
	v_mul_f32_e32 v76, 0x45800000, v63
	v_cndmask_b32_e32 v63, v63, v76, vcc
	v_mul_f32_e32 v76, v110, v63
	v_mul_f32_e32 v76, v76, v60
	v_cvt_pk_bf16_f32 v80, v76, s0
	v_add_co_u32_e32 v76, vcc, s67, v30
	v_pk_mul_f32 v[22:23], v[10:11], v[10:11]
	s_nop 0
	v_addc_co_u32_e32 v77, vcc, 0, v31, vcc
	global_store_short v[76:77], v80, off
	v_mul_f32_e32 v80, v111, v63
	v_mul_f32_e32 v80, v80, v61
	v_cvt_pk_bf16_f32 v80, v80, s0
	global_store_short v[76:77], v80, off offset:64
	v_mul_f32_e32 v80, v112, v63
	v_mul_f32_e32 v80, v80, v47
	v_cvt_pk_bf16_f32 v80, v80, s0
	global_store_short v[76:77], v80, off offset:128
	v_mov_b32_e32 v80, v122
	v_pk_add_f32 v[80:81], v[80:81], v[116:117]
	v_mul_f32_e32 v63, v113, v63
	v_pk_add_f32 v[80:81], v[80:81], v[98:99]
	v_mul_f32_e32 v63, v63, v46
	v_pk_add_f32 v[80:81], v[80:81], v[120:121]
	s_nop 1
	v_mov_b32_dpp v99, v81 quad_perm:[1,0,3,2] row_mask:0xf bank_mask:0xf
	s_nop 1
	v_mov_b32_dpp v98, v80 quad_perm:[1,0,3,2] row_mask:0xf bank_mask:0xf
	v_cvt_pk_bf16_f32 v102, v63, s0
	v_mul_f32_e32 v63, 0x4b800000, v62
	v_cmp_gt_f32_e32 vcc, s62, v62
	global_store_short v[76:77], v102, off offset:192
	v_pk_mul_f32 v[28:29], v[6:7], v[6:7]
	v_cndmask_b32_e32 v62, v62, v63, vcc
	v_rsq_f32_e32 v103, v62
	s_waitcnt lgkmcnt(0)
	v_pk_add_f32 v[62:63], v[80:81], v[98:99]
	s_nop 1
	v_mov_b32_dpp v81, v63 quad_perm:[2,3,0,1] row_mask:0xf bank_mask:0xf
	s_nop 1
	v_mov_b32_dpp v80, v62 quad_perm:[2,3,0,1] row_mask:0xf bank_mask:0xf
	v_mul_f32_e32 v98, 0x45800000, v103
	v_cndmask_b32_e32 v98, v103, v98, vcc
	v_mul_f32_e32 v96, v96, v98
	v_mul_f32_e32 v90, v90, v98
	s_waitcnt lgkmcnt(0)
	v_pk_add_f32 v[62:63], v[62:63], v[80:81]
	s_nop 1
	v_mov_b32_dpp v81, v63 row_half_mirror row_mask:0xf bank_mask:0xf
	s_nop 1
	v_mov_b32_dpp v80, v62 row_half_mirror row_mask:0xf bank_mask:0xf
	v_mul_f32_e32 v96, v96, v60
	v_mul_f32_e32 v90, v90, v47
	v_cvt_pk_bf16_f32 v96, v96, s0
	v_cvt_pk_bf16_f32 v90, v90, s0
	s_waitcnt lgkmcnt(0)
; __device__ __forceinline__ int crow(int r, int hi) { return (r & 3) + 8 * (r >> 2) + 4 * hi; }
; template <int MODE>
; __device__ __forceinline__ void attn_unit(const UnitArgs& A, char* lds, const int wave_) {
;     ...
;             for (int r = 0; r < 16; ++r) { float v = ssq[r]; v = bfly_add<1>(v); v = bfly_add<2>(v); v = bfly_add<4>(v); v = bfly_add<8>(v); v = bfly_add<16>(v); ssq[r] = v; }
;             float gv[4];
; #pragma unroll
;             for (int d0 = 0; d0 < 4; ++d0) gv[d0] = A.subg[d0 * 32 + r32] * A.oscale;
;             __hip_bfloat16* Ow = (__hip_bfloat16*)A.Ob + (long)(qb * QBLK) * DM;
; #pragma unroll
;             for (int r = 0; r < 16; ++r) { const float rn = rsqrtf(ssq[r] * (1.f / 128.f) + EPS); const int orow = crow(r, hi);
; #pragma unroll
;                 for (int d0 = 0; d0 < 4; ++d0) Ow[(long)orow * DM + d0 * 32 + r32] = __float2bfloat16(o[d0][r] * rn * gv[d0]); }
	v_pk_add_f32 v[62:63], v[62:63], v[80:81]
	s_nop 1
	v_mov_b32_dpp v81, v63 row_mirror row_mask:0xf bank_mask:0xf
	s_nop 1
	v_mov_b32_dpp v80, v62 row_mirror row_mask:0xf bank_mask:0xf
	global_store_short v[76:77], v96, off offset:2048
	v_mul_f32_e32 v96, v97, v98
	global_store_short v[76:77], v90, off offset:2176
	v_mul_f32_e32 v90, v91, v98
	s_waitcnt lgkmcnt(0)
	v_pk_add_f32 v[62:63], v[62:63], v[80:81]
	v_mov_b32_e32 v81, v63
	s_nop 1
	v_permlane16_swap_b32_e32 v63, v81
	v_mov_b32_e32 v80, v62
	s_nop 1
	v_permlane16_swap_b32_e32 v62, v80
	v_mul_f32_e32 v96, v96, v61
	v_cvt_pk_bf16_f32 v96, v96, s0
	global_store_short v[76:77], v96, off offset:2112
	s_waitcnt lgkmcnt(0)
	v_pk_add_f32 v[62:63], v[62:63], v[80:81]
	s_nop 0
	v_pk_fma_f32 v[62:63], v[62:63], s[2:3], v[14:15] op_sel_hi:[1,0,0]
	s_nop 0
	v_mul_f32_e32 v80, 0x4b800000, v63
	v_cmp_gt_f32_e32 vcc, s62, v63
	s_nop 1
	v_cndmask_b32_e32 v63, v63, v80, vcc
	v_rsq_f32_e32 v63, v63
	v_mul_f32_e32 v80, v90, v46
	v_cvt_pk_bf16_f32 v80, v80, s0
	global_store_short v[76:77], v80, off offset:2240
	v_mul_f32_e32 v76, 0x45800000, v63
	v_cndmask_b32_e32 v63, v63, v76, vcc
	v_mul_f32_e32 v76, v82, v63
	v_mul_f32_e32 v76, v76, v60
	v_cvt_pk_bf16_f32 v82, v76, s0
	v_add_co_u32_e32 v76, vcc, s59, v30
	s_nop 1
	v_addc_co_u32_e32 v77, vcc, 0, v31, vcc
	v_add_co_u32_e32 v80, vcc, s68, v30
	s_nop 1
	v_addc_co_u32_e32 v81, vcc, 0, v31, vcc
	global_store_short v[80:81], v82, off offset:-4096
	v_mul_f32_e32 v82, v83, v63
	v_mul_f32_e32 v82, v82, v61
	v_cvt_pk_bf16_f32 v82, v82, s0
	global_store_short v[76:77], v82, off offset:64
	v_mul_f32_e32 v82, v84, v63
	v_mul_f32_e32 v82, v82, v47
	v_cvt_pk_bf16_f32 v82, v82, s0
	global_store_short v[76:77], v82, off offset:128
	v_mov_b32_e32 v82, v106
	v_mov_b32_e32 v83, v86
	v_mov_b32_e32 v86, v107
	v_mul_f32_e32 v63, v85, v63
	v_pk_add_f32 v[82:83], v[82:83], v[86:87]
	v_mov_b32_e32 v84, v108
	v_mov_b32_e32 v85, v94
	v_pk_add_f32 v[82:83], v[82:83], v[84:85]
	v_mov_b32_e32 v94, v109
	v_pk_add_f32 v[82:83], v[82:83], v[94:95]
	s_nop 1
	v_mov_b32_dpp v85, v83 quad_perm:[1,0,3,2] row_mask:0xf bank_mask:0xf
	s_nop 1
	v_mov_b32_dpp v84, v82 quad_perm:[1,0,3,2] row_mask:0xf bank_mask:0xf
	v_mul_f32_e32 v63, v63, v46
	v_cvt_pk_bf16_f32 v90, v63, s0
	v_mul_f32_e32 v63, 0x4b800000, v62
	v_cmp_gt_f32_e32 vcc, s62, v62
	global_store_short v[76:77], v90, off offset:192
	s_nop 0
	v_cndmask_b32_e32 v62, v62, v63, vcc
	v_rsq_f32_e32 v86, v62
	s_waitcnt lgkmcnt(0)
	v_pk_add_f32 v[62:63], v[82:83], v[84:85]
	s_nop 1
	v_mov_b32_dpp v83, v63 quad_perm:[2,3,0,1] row_mask:0xf bank_mask:0xf
	s_nop 1
	v_mov_b32_dpp v82, v62 quad_perm:[2,3,0,1] row_mask:0xf bank_mask:0xf
	v_mul_f32_e32 v84, 0x45800000, v86
	v_cndmask_b32_e32 v84, v86, v84, vcc
	v_mul_f32_e32 v68, v68, v84
	v_mul_f32_e32 v68, v68, v60
	s_waitcnt lgkmcnt(0)
	v_pk_add_f32 v[62:63], v[62:63], v[82:83]
	s_nop 1
	v_mov_b32_dpp v83, v63 row_half_mirror row_mask:0xf bank_mask:0xf
	s_nop 1
	v_mov_b32_dpp v82, v62 row_half_mirror row_mask:0xf bank_mask:0xf
	v_cvt_pk_bf16_f32 v68, v68, s0
	global_store_short v[76:77], v68, off offset:2048
	v_mul_f32_e32 v85, v69, v84
	v_mul_f32_e32 v66, v66, v84
	s_waitcnt lgkmcnt(0)
	v_pk_add_f32 v[62:63], v[62:63], v[82:83]
	s_nop 1
	v_mov_b32_dpp v69, v63 row_mirror row_mask:0xf bank_mask:0xf
	s_nop 1
	v_mov_b32_dpp v68, v62 row_mirror row_mask:0xf bank_mask:0xf
	v_mul_f32_e32 v66, v66, v47
	v_cvt_pk_bf16_f32 v66, v66, s0
	global_store_short v[76:77], v66, off offset:2176
	v_mul_f32_e32 v66, v67, v84
	s_waitcnt lgkmcnt(0)
	v_pk_add_f32 v[62:63], v[62:63], v[68:69]
	v_mov_b32_e32 v69, v63
	s_nop 1
	v_permlane16_swap_b32_e32 v63, v69
	v_mov_b32_e32 v68, v62
	s_nop 1
	v_permlane16_swap_b32_e32 v62, v68
	v_mul_f32_e32 v66, v66, v46
	v_cvt_pk_bf16_f32 v66, v66, s0
	global_store_short v[76:77], v66, off offset:2240
	v_mul_f32_e32 v82, v85, v61
	s_waitcnt lgkmcnt(0)
	v_pk_add_f32 v[62:63], v[62:63], v[68:69]
	v_cvt_pk_bf16_f32 v82, v82, s0
	v_pk_fma_f32 v[62:63], v[62:63], s[2:3], v[14:15] op_sel_hi:[1,0,0]
	global_store_short v[76:77], v82, off offset:2112
	v_mul_f32_e32 v67, 0x4b800000, v63
	v_cmp_gt_f32_e32 vcc, s62, v63
	s_nop 1
	v_cndmask_b32_e32 v63, v63, v67, vcc
	v_rsq_f32_e32 v63, v63
	s_nop 0
	v_mul_f32_e32 v66, 0x45800000, v63
	v_cndmask_b32_e32 v63, v63, v66, vcc
	v_mul_f32_e32 v52, v52, v63
	v_mul_f32_e32 v52, v52, v60
	v_cvt_pk_bf16_f32 v52, v52, s0
	global_store_short v[80:81], v52, off
	v_mul_f32_e32 v52, v53, v63
	v_mul_f32_e32 v52, v52, v61
	v_cvt_pk_bf16_f32 v52, v52, s0
	global_store_short v[80:81], v52, off offset:64
	v_mul_f32_e32 v52, v64, v63
	v_mul_f32_e32 v52, v52, v47
	v_cvt_pk_bf16_f32 v52, v52, s0
	global_store_short v[80:81], v52, off offset:128
	v_mul_f32_e32 v52, v65, v63
	v_mul_f32_e32 v52, v52, v46
	v_cvt_pk_bf16_f32 v66, v52, s0
	v_mov_b32_e32 v52, v78
	v_mov_b32_e32 v53, v72
	v_mov_b32_e32 v72, v79
	v_pk_add_f32 v[52:53], v[52:53], v[72:73]
	v_mov_b32_e32 v64, v126
	v_mov_b32_e32 v65, v74
	v_pk_add_f32 v[52:53], v[52:53], v[64:65]
	v_mov_b32_e32 v74, v127
	v_pk_add_f32 v[52:53], v[52:53], v[74:75]
	s_nop 1
	v_mov_b32_dpp v65, v53 quad_perm:[1,0,3,2] row_mask:0xf bank_mask:0xf
	s_nop 1
	v_mov_b32_dpp v64, v52 quad_perm:[1,0,3,2] row_mask:0xf bank_mask:0xf
	v_mul_f32_e32 v63, 0x4b800000, v62
	v_cmp_gt_f32_e32 vcc, s62, v62
	global_store_short v[80:81], v66, off offset:192
	s_waitcnt lgkmcnt(0)
	v_pk_add_f32 v[52:53], v[52:53], v[64:65]
	v_cndmask_b32_e32 v62, v62, v63, vcc
	v_rsq_f32_e32 v67, v62
	s_nop 1
	v_mov_b32_dpp v63, v53 quad_perm:[2,3,0,1] row_mask:0xf bank_mask:0xf
	s_nop 1
	v_mov_b32_dpp v62, v52 quad_perm:[2,3,0,1] row_mask:0xf bank_mask:0xf
	v_mul_f32_e32 v64, 0x45800000, v67
	v_cndmask_b32_e32 v64, v67, v64, vcc
	v_mul_f32_e32 v48, v48, v64
	s_waitcnt lgkmcnt(0)
; __device__ __forceinline__ int crow(int r, int hi) { return (r & 3) + 8 * (r >> 2) + 4 * hi; }
; template <int MODE>
; __device__ __forceinline__ void attn_unit(const UnitArgs& A, char* lds, const int wave_) {
;     ...
;             for (int r = 0; r < 16; ++r) { float v = ssq[r]; v = bfly_add<1>(v); v = bfly_add<2>(v); v = bfly_add<4>(v); v = bfly_add<8>(v); v = bfly_add<16>(v); ssq[r] = v; }
;             float gv[4];
; #pragma unroll
;             for (int d0 = 0; d0 < 4; ++d0) gv[d0] = A.subg[d0 * 32 + r32] * A.oscale;
;             __hip_bfloat16* Ow = (__hip_bfloat16*)A.Ob + (long)(qb * QBLK) * DM;
; #pragma unroll
;             for (int r = 0; r < 16; ++r) { const float rn = rsqrtf(ssq[r] * (1.f / 128.f) + EPS); const int orow = crow(r, hi);
; #pragma unroll
;                 for (int d0 = 0; d0 < 4; ++d0) Ow[(long)orow * DM + d0 * 32 + r32] = __float2bfloat16(o[d0][r] * rn * gv[d0]); }
	v_pk_add_f32 v[52:53], v[52:53], v[62:63]
	s_nop 1
	v_mov_b32_dpp v63, v53 row_half_mirror row_mask:0xf bank_mask:0xf
	s_nop 1
	v_mov_b32_dpp v62, v52 row_half_mirror row_mask:0xf bank_mask:0xf
	v_mul_f32_e32 v48, v48, v60
	v_cvt_pk_bf16_f32 v48, v48, s0
	global_store_short v[80:81], v48, off offset:2048
	v_mul_f32_e32 v65, v49, v64
	s_waitcnt lgkmcnt(0)
	v_pk_add_f32 v[48:49], v[52:53], v[62:63]
	s_nop 1
	v_mov_b32_dpp v53, v49 row_mirror row_mask:0xf bank_mask:0xf
	s_nop 1
	v_mov_b32_dpp v52, v48 row_mirror row_mask:0xf bank_mask:0xf
	v_mul_f32_e32 v38, v38, v64
	v_mul_f32_e32 v62, v65, v61
	v_mul_f32_e32 v38, v38, v47
	v_cvt_pk_bf16_f32 v62, v62, s0
	s_waitcnt lgkmcnt(0)
	v_pk_add_f32 v[48:49], v[48:49], v[52:53]
	v_mov_b32_e32 v53, v49
	s_nop 1
	v_permlane16_swap_b32_e32 v49, v53
	v_mov_b32_e32 v52, v48
	s_nop 1
	v_permlane16_swap_b32_e32 v48, v52
	v_cvt_pk_bf16_f32 v38, v38, s0
	global_store_short v[80:81], v62, off offset:2112
	global_store_short v[80:81], v38, off offset:2176
	v_mul_f32_e32 v62, v39, v64
	s_waitcnt lgkmcnt(0)
	v_pk_add_f32 v[38:39], v[48:49], v[52:53]
	s_nop 0
	v_pk_fma_f32 v[38:39], v[38:39], s[2:3], v[14:15] op_sel_hi:[1,0,0]
	s_nop 0
	v_mul_f32_e32 v48, 0x4b800000, v39
	v_cmp_gt_f32_e32 vcc, s62, v39
	s_nop 1
	v_cndmask_b32_e32 v39, v39, v48, vcc
	v_rsq_f32_e32 v39, v39
	v_mul_f32_e32 v48, v62, v46
	v_cvt_pk_bf16_f32 v48, v48, s0
	global_store_short v[80:81], v48, off offset:2240
	v_mul_f32_e32 v48, 0x45800000, v39
	v_cndmask_b32_e32 v39, v39, v48, vcc
	v_add_co_u32_e32 v48, vcc, s60, v30
	v_mul_f32_e32 v32, v32, v39
	s_nop 0
	v_addc_co_u32_e32 v49, vcc, 0, v31, vcc
	v_mul_f32_e32 v32, v32, v60
	v_add_co_u32_e32 v52, vcc, s69, v30
	v_cvt_pk_bf16_f32 v32, v32, s0
	s_nop 0
	v_addc_co_u32_e32 v53, vcc, 0, v31, vcc
	global_store_short v[52:53], v32, off offset:-4096
	v_mul_f32_e32 v32, v33, v39
	v_mul_f32_e32 v32, v32, v61
	v_cvt_pk_bf16_f32 v32, v32, s0
	global_store_short v[48:49], v32, off offset:64
	v_mul_f32_e32 v32, v34, v39
	v_mul_f32_e32 v32, v32, v47
	v_cvt_pk_bf16_f32 v32, v32, s0
	global_store_short v[48:49], v32, off offset:128
	v_mul_f32_e32 v32, v35, v39
	v_mul_f32_e32 v32, v32, v46
	v_cvt_pk_bf16_f32 v39, v32, s0
	v_mov_b32_e32 v32, v100
	v_mov_b32_e32 v33, v92
	v_mov_b32_e32 v92, v101
	v_pk_add_f32 v[32:33], v[32:33], v[92:93]
	v_mov_b32_e32 v34, v58
	v_mov_b32_e32 v35, v88
	v_pk_add_f32 v[32:33], v[32:33], v[34:35]
	v_mov_b32_e32 v88, v59
	v_pk_add_f32 v[32:33], v[32:33], v[88:89]
	s_nop 1
	v_mov_b32_dpp v35, v33 quad_perm:[1,0,3,2] row_mask:0xf bank_mask:0xf
	s_nop 1
	v_mov_b32_dpp v34, v32 quad_perm:[1,0,3,2] row_mask:0xf bank_mask:0xf
	v_mul_f32_e32 v58, 0x4b800000, v38
	v_cmp_gt_f32_e32 vcc, s62, v38
	global_store_short v[48:49], v39, off offset:192
	s_waitcnt lgkmcnt(0)
	v_pk_add_f32 v[32:33], v[32:33], v[34:35]
	s_nop 1
	v_mov_b32_dpp v35, v33 quad_perm:[2,3,0,1] row_mask:0xf bank_mask:0xf
	s_nop 1
	v_mov_b32_dpp v34, v32 quad_perm:[2,3,0,1] row_mask:0xf bank_mask:0xf
	v_cndmask_b32_e32 v38, v38, v58, vcc
	v_rsq_f32_e32 v38, v38
	s_waitcnt lgkmcnt(0)
	v_pk_add_f32 v[32:33], v[32:33], v[34:35]
	v_mul_f32_e32 v39, 0x45800000, v38
	s_nop 1
	v_mov_b32_dpp v35, v33 row_half_mirror row_mask:0xf bank_mask:0xf
	s_nop 1
	v_mov_b32_dpp v34, v32 row_half_mirror row_mask:0xf bank_mask:0xf
	v_cndmask_b32_e32 v38, v38, v39, vcc
	v_mul_f32_e32 v16, v16, v38
	v_mul_f32_e32 v16, v16, v60
	v_cvt_pk_bf16_f32 v16, v16, s0
	global_store_short v[48:49], v16, off offset:2048
	v_mul_f32_e32 v39, v17, v38
	s_waitcnt lgkmcnt(0)
	v_pk_add_f32 v[16:17], v[32:33], v[34:35]
	s_nop 1
	v_mov_b32_dpp v33, v17 row_mirror row_mask:0xf bank_mask:0xf
	s_nop 1
	v_mov_b32_dpp v32, v16 row_mirror row_mask:0xf bank_mask:0xf
	v_mul_f32_e32 v34, v39, v61
	v_cvt_pk_bf16_f32 v34, v34, s0
	global_store_short v[48:49], v34, off offset:2112
	v_mul_f32_e32 v34, v70, v38
	s_waitcnt lgkmcnt(0)
	v_pk_add_f32 v[16:17], v[16:17], v[32:33]
	v_mov_b32_e32 v33, v17
	s_nop 1
	v_permlane16_swap_b32_e32 v17, v33
	v_mov_b32_e32 v32, v16
	s_nop 1
	v_permlane16_swap_b32_e32 v16, v32
	v_mul_f32_e32 v34, v34, v47
	v_cvt_pk_bf16_f32 v34, v34, s0
	global_store_short v[48:49], v34, off offset:2176
	v_mul_f32_e32 v34, v71, v38
	s_waitcnt lgkmcnt(0)
	v_pk_add_f32 v[16:17], v[16:17], v[32:33]
	v_mov_b32_e32 v33, v42
	v_pk_fma_f32 v[16:17], v[16:17], s[2:3], v[14:15] op_sel_hi:[1,0,0]
	v_mov_b32_e32 v42, v51
	v_mul_f32_e32 v32, 0x4b800000, v17
	v_cmp_gt_f32_e32 vcc, s62, v17
	v_mov_b32_e32 v35, v40
	v_mov_b32_e32 v40, v45
	v_cndmask_b32_e32 v17, v17, v32, vcc
	v_rsq_f32_e32 v17, v17
	v_mul_f32_e32 v32, v34, v46
	v_cvt_pk_bf16_f32 v32, v32, s0
	global_store_short v[48:49], v32, off offset:2240
	v_mul_f32_e32 v32, 0x45800000, v17
	v_cndmask_b32_e32 v17, v17, v32, vcc
	v_mul_f32_e32 v32, v56, v17
	v_mul_f32_e32 v32, v32, v60
	v_cvt_pk_bf16_f32 v32, v32, s0
	global_store_short v[52:53], v32, off
	v_mul_f32_e32 v32, v57, v17
	v_mul_f32_e32 v32, v32, v61
	v_cvt_pk_bf16_f32 v32, v32, s0
	global_store_short v[52:53], v32, off offset:64
	v_mul_f32_e32 v32, v54, v17
	v_mul_f32_e32 v32, v32, v47
	v_cvt_pk_bf16_f32 v32, v32, s0
	global_store_short v[52:53], v32, off offset:128
	v_mov_b32_e32 v32, v50
	v_pk_add_f32 v[32:33], v[32:33], v[42:43]
	v_mov_b32_e32 v34, v44
	v_pk_add_f32 v[32:33], v[32:33], v[34:35]
	v_mul_f32_e32 v17, v55, v17
	v_pk_add_f32 v[32:33], v[32:33], v[40:41]
	s_nop 1
	v_mov_b32_dpp v35, v33 quad_perm:[1,0,3,2] row_mask:0xf bank_mask:0xf
	s_nop 1
	v_mov_b32_dpp v34, v32 quad_perm:[1,0,3,2] row_mask:0xf bank_mask:0xf
	v_mul_f32_e32 v17, v17, v46
	v_cvt_pk_bf16_f32 v38, v17, s0
	v_mul_f32_e32 v17, 0x4b800000, v16
	v_cmp_gt_f32_e32 vcc, s62, v16
	global_store_short v[52:53], v38, off offset:192
	s_nop 0
	v_cndmask_b32_e32 v16, v16, v17, vcc
	v_rsq_f32_e32 v39, v16
	s_waitcnt lgkmcnt(0)
; __device__ __forceinline__ int crow(int r, int hi) { return (r & 3) + 8 * (r >> 2) + 4 * hi; }
; template <int MODE>
; __device__ __forceinline__ void attn_unit(const UnitArgs& A, char* lds, const int wave_) {
;     ...
;             for (int r = 0; r < 16; ++r) { float v = ssq[r]; v = bfly_add<1>(v); v = bfly_add<2>(v); v = bfly_add<4>(v); v = bfly_add<8>(v); v = bfly_add<16>(v); ssq[r] = v; }
;             float gv[4];
; #pragma unroll
;             for (int d0 = 0; d0 < 4; ++d0) gv[d0] = A.subg[d0 * 32 + r32] * A.oscale;
;             __hip_bfloat16* Ow = (__hip_bfloat16*)A.Ob + (long)(qb * QBLK) * DM;
; #pragma unroll
;             for (int r = 0; r < 16; ++r) { const float rn = rsqrtf(ssq[r] * (1.f / 128.f) + EPS); const int orow = crow(r, hi);
; #pragma unroll
;                 for (int d0 = 0; d0 < 4; ++d0) Ow[(long)orow * DM + d0 * 32 + r32] = __float2bfloat16(o[d0][r] * rn * gv[d0]); }
	v_pk_add_f32 v[16:17], v[32:33], v[34:35]
	s_nop 1
	v_mov_b32_dpp v33, v17 quad_perm:[2,3,0,1] row_mask:0xf bank_mask:0xf
	s_nop 1
	v_mov_b32_dpp v32, v16 quad_perm:[2,3,0,1] row_mask:0xf bank_mask:0xf
	v_mul_f32_e32 v34, 0x45800000, v39
	v_cndmask_b32_e32 v34, v39, v34, vcc
	v_mul_f32_e32 v24, v24, v34
	v_mul_f32_e32 v24, v24, v47
	s_waitcnt lgkmcnt(0)
	v_pk_add_f32 v[16:17], v[16:17], v[32:33]
	s_nop 1
	v_mov_b32_dpp v33, v17 row_half_mirror row_mask:0xf bank_mask:0xf
	s_nop 1
	v_mov_b32_dpp v32, v16 row_half_mirror row_mask:0xf bank_mask:0xf
	v_cvt_pk_bf16_f32 v24, v24, s0
	global_store_short v[52:53], v24, off offset:2176
	v_mul_f32_e32 v24, v25, v34
	v_mul_f32_e32 v24, v24, v46
	s_waitcnt lgkmcnt(0)
	v_pk_add_f32 v[16:17], v[16:17], v[32:33]
	s_nop 1
	v_mov_b32_dpp v33, v17 row_mirror row_mask:0xf bank_mask:0xf
	s_nop 1
	v_mov_b32_dpp v32, v16 row_mirror row_mask:0xf bank_mask:0xf
	v_cvt_pk_bf16_f32 v24, v24, s0
	global_store_short v[52:53], v24, off offset:2240
	v_mul_f32_e32 v35, v36, v34
	v_mul_f32_e32 v35, v35, v60
	s_waitcnt lgkmcnt(0)
	v_pk_add_f32 v[16:17], v[16:17], v[32:33]
	v_mov_b32_e32 v33, v17
	s_nop 1
	v_permlane16_swap_b32_e32 v17, v33
	v_mov_b32_e32 v32, v16
	s_nop 1
	v_permlane16_swap_b32_e32 v16, v32
	v_cvt_pk_bf16_f32 v35, v35, s0
	global_store_short v[52:53], v35, off offset:2048
	v_mul_f32_e32 v35, v37, v34
	v_mul_f32_e32 v35, v35, v61
	s_waitcnt lgkmcnt(0)
	v_pk_add_f32 v[16:17], v[16:17], v[32:33]
	v_cvt_pk_bf16_f32 v35, v35, s0
	v_pk_fma_f32 v[16:17], v[16:17], s[2:3], v[14:15] op_sel_hi:[1,0,0]
	global_store_short v[52:53], v35, off offset:2112
	v_mul_f32_e32 v25, 0x4b800000, v17
	v_cmp_gt_f32_e32 vcc, s62, v17
	s_nop 1
	v_cndmask_b32_e32 v17, v17, v25, vcc
	v_rsq_f32_e32 v17, v17
	s_nop 0
	v_mul_f32_e32 v24, 0x45800000, v17
	v_cndmask_b32_e32 v17, v17, v24, vcc
	v_add_co_u32_e32 v24, vcc, s61, v30
	v_mul_f32_e32 v20, v20, v17
	s_nop 0
	v_addc_co_u32_e32 v25, vcc, 0, v31, vcc
	v_mul_f32_e32 v18, v18, v17
	v_mul_f32_e32 v20, v20, v60
	v_add_co_u32_e32 v30, vcc, s72, v30
	v_mul_f32_e32 v18, v18, v47
	v_cvt_pk_bf16_f32 v20, v20, s0
	v_addc_co_u32_e32 v31, vcc, 0, v31, vcc
	v_cvt_pk_bf16_f32 v18, v18, s0
	global_store_short v[30:31], v20, off offset:-4096
	v_mul_f32_e32 v20, v21, v17
	global_store_short v[24:25], v18, off offset:128
	v_mul_f32_e32 v17, v19, v17
	v_mov_b32_e32 v18, v26
	v_mov_b32_e32 v19, v12
	v_mov_b32_e32 v12, v27
	v_pk_add_f32 v[12:13], v[18:19], v[12:13]
	v_mov_b32_e32 v18, v28
	v_mov_b32_e32 v19, v22
	v_pk_add_f32 v[12:13], v[12:13], v[18:19]
	v_mov_b32_e32 v22, v29
	v_pk_add_f32 v[12:13], v[12:13], v[22:23]
	s_nop 1
	v_mov_b32_dpp v19, v13 quad_perm:[1,0,3,2] row_mask:0xf bank_mask:0xf
	s_nop 1
	v_mov_b32_dpp v18, v12 quad_perm:[1,0,3,2] row_mask:0xf bank_mask:0xf
	v_mul_f32_e32 v20, v20, v61
	v_cvt_pk_bf16_f32 v20, v20, s0
	v_mul_f32_e32 v17, v17, v46
	global_store_short v[24:25], v20, off offset:64
	v_cvt_pk_bf16_f32 v20, v17, s0
	v_mul_f32_e32 v17, 0x4b800000, v16
	v_cmp_gt_f32_e32 vcc, s62, v16
	s_waitcnt lgkmcnt(0)
	v_pk_add_f32 v[12:13], v[12:13], v[18:19]
	global_store_short v[24:25], v20, off offset:192
	v_cndmask_b32_e32 v16, v16, v17, vcc
	v_rsq_f32_e32 v21, v16
	s_nop 1
	v_mov_b32_dpp v17, v13 quad_perm:[2,3,0,1] row_mask:0xf bank_mask:0xf
	s_nop 1
	v_mov_b32_dpp v16, v12 quad_perm:[2,3,0,1] row_mask:0xf bank_mask:0xf
	v_mul_f32_e32 v18, 0x45800000, v21
	v_cndmask_b32_e32 v18, v21, v18, vcc
	v_mul_f32_e32 v8, v8, v18
	s_waitcnt lgkmcnt(0)
	v_pk_add_f32 v[12:13], v[12:13], v[16:17]
	s_nop 1
	v_mov_b32_dpp v17, v13 row_half_mirror row_mask:0xf bank_mask:0xf
	s_nop 1
	v_mov_b32_dpp v16, v12 row_half_mirror row_mask:0xf bank_mask:0xf
	v_mul_f32_e32 v8, v8, v60
	v_cvt_pk_bf16_f32 v8, v8, s0
	global_store_short v[24:25], v8, off offset:2048
	v_mul_f32_e32 v19, v9, v18
	s_waitcnt lgkmcnt(0)
	v_pk_add_f32 v[8:9], v[12:13], v[16:17]
	s_nop 1
	v_mov_b32_dpp v13, v9 row_mirror row_mask:0xf bank_mask:0xf
	s_nop 1
	v_mov_b32_dpp v12, v8 row_mirror row_mask:0xf bank_mask:0xf
	v_mul_f32_e32 v2, v2, v18
	v_mul_f32_e32 v16, v19, v61
	v_mul_f32_e32 v2, v2, v47
	v_cvt_pk_bf16_f32 v16, v16, s0
	s_waitcnt lgkmcnt(0)
	v_pk_add_f32 v[8:9], v[8:9], v[12:13]
	ds_swizzle_b32 v13, v9 offset:swizzle(SWAP,16)
	v_mov_b32_e32 v12, v8
	s_nop 1
	v_permlane16_swap_b32_e32 v8, v12
	v_cvt_pk_bf16_f32 v2, v2, s0
	global_store_short v[24:25], v16, off offset:2112
	global_store_short v[24:25], v2, off offset:2176
	v_mul_f32_e32 v16, v3, v18
	s_waitcnt lgkmcnt(0)
	v_pk_add_f32 v[2:3], v[8:9], v[12:13]
	s_nop 0
	v_pk_fma_f32 v[2:3], v[2:3], s[2:3], v[14:15] op_sel_hi:[1,0,0]
	s_nop 0
	v_mul_f32_e32 v8, 0x4b800000, v3
	v_cmp_gt_f32_e32 vcc, s62, v3
	s_nop 1
	v_cndmask_b32_e32 v3, v3, v8, vcc
	v_rsq_f32_e32 v3, v3
	v_mul_f32_e32 v8, v16, v46
	v_cvt_pk_bf16_f32 v8, v8, s0
	global_store_short v[24:25], v8, off offset:2240
	v_mul_f32_e32 v8, 0x45800000, v3
	v_cndmask_b32_e32 v3, v3, v8, vcc
	v_mul_f32_e32 v0, v0, v3
	v_mul_f32_e32 v0, v60, v0
	v_cvt_pk_bf16_f32 v0, v0, s0
	global_store_short v[30:31], v0, off
	v_mul_f32_e32 v0, v1, v3
	v_mul_f32_e32 v0, v61, v0
	v_cvt_pk_bf16_f32 v0, v0, s0
	global_store_short v[30:31], v0, off offset:64
	v_mul_f32_e32 v0, v10, v3
	v_mul_f32_e32 v1, 0x4b800000, v2
	v_cmp_gt_f32_e32 vcc, s62, v2
	v_mul_f32_e32 v0, v47, v0
	v_cvt_pk_bf16_f32 v0, v0, s0
	v_cndmask_b32_e32 v1, v2, v1, vcc
	v_rsq_f32_e32 v1, v1
	global_store_short v[30:31], v0, off offset:128
	v_mul_f32_e32 v0, v11, v3
	v_mul_f32_e32 v0, v46, v0
	v_cvt_pk_bf16_f32 v0, v0, s0
	global_store_short v[30:31], v0, off offset:192
	v_mul_f32_e32 v0, 0x45800000, v1
	v_cndmask_b32_e32 v0, v1, v0, vcc
	v_mul_f32_e32 v1, v4, v0
	v_mul_f32_e32 v1, v60, v1
	v_cvt_pk_bf16_f32 v1, v1, s0
	global_store_short v[30:31], v1, off offset:2048
	v_mul_f32_e32 v1, v5, v0
	v_mul_f32_e32 v1, v61, v1
	v_cvt_pk_bf16_f32 v1, v1, s0
	global_store_short v[30:31], v1, off offset:2112
	v_mul_f32_e32 v1, v6, v0
	v_mul_f32_e32 v0, v7, v0
	v_mul_f32_e32 v1, v47, v1
	v_mul_f32_e32 v0, v46, v0
	v_cvt_pk_bf16_f32 v1, v1, s0
	v_cvt_pk_bf16_f32 v0, v0, s0
	global_store_short v[30:31], v1, off offset:2176
	global_store_short v[30:31], v0, off offset:2240
	s_branch .LBB0_307

; #define PG8_ABASE(pm_) (HALO ? ((const char*)Ag + ((long)halo_row0(pm_)) * (long)K * 2) : ((const char*)Ag + (size_t)(pm_) * 2 * hstepB))
; template <class Epi, bool HALO>
; __device__ __forceinline__ void gemm_phase(LAS unsigned char* lds, const bf16_t* Ag, const bf16_t* Btg, const int K, const int nM, const int nN, const int G, const int cidx, const int wave_, const Epi& E) {
;     ...
;         const bool has_next = S.next(ui + 1, nxt);
;         const char* nA = has_next ? PG8_ABASE(nxt.pm) : cA; const char* nB = has_next ? PG8_BBASE(nxt.pn) : cB;
;         for (int t = 0; t < nt; t += 2) {
;             const bool last = (t == nt - 2);
;             const char* a1 = cA + (size_t)(t + 1) * kstep;
;             const char* a2 = last ? nA : cA + (size_t)(t + 2) * kstep; const char* b2 = last ? nB : cB + (size_t)(t + 2) * kstep;
;     ...
; #pragma unroll
;         for (int a = 0; a < 2; ++a)
; #pragma unroll
;             for (int b = 0; b < 2; ++b)
; #pragma unroll
;                 for (int m = 0; m < 4; ++m)
; #pragma unroll
;                     for (int n = 0; n < 2; ++n) acc[a][b][m][n] = (f32x4){0.f, 0.f, 0.f, 0.f};
.LBB0_696:
	s_ashr_i32 s19, s18, 31
	s_lshl_b64 s[20:21], s[18:19], 19
	s_add_u32 s20, s0, s20
	s_addc_u32 s21, s1, s21
	s_and_b64 s[22:23], s[6:7], exec
	s_cselect_b32 s19, s21, s25
	s_cselect_b32 s44, s20, s24
	s_ashr_i32 s15, s14, 31
	s_lshl_b64 s[22:23], s[14:15], 19
	s_add_u32 s22, s30, s22
	s_addc_u32 s23, s31, s23
	s_and_b64 s[28:29], s[6:7], exec
	s_cselect_b32 s15, s23, s27
	s_cselect_b32 s45, s22, s26
	s_add_u32 s24, s24, 0x40080
	s_addc_u32 s25, s25, 0
	s_add_u32 s46, s26, 0x100
	v_mov_b32_e32 v0, 0
	s_addc_u32 s47, s27, 0
	s_mov_b32 s48, -2
	v_mov_b64_e32 v[0:1], 0
	v_mov_b64_e32 v[2:3], 0
	v_mov_b64_e32 v[4:5], 0
	v_mov_b64_e32 v[6:7], 0
	v_mov_b64_e32 v[8:9], 0
	v_mov_b64_e32 v[10:11], 0
	v_mov_b64_e32 v[12:13], 0
	v_mov_b64_e32 v[14:15], 0
	v_mov_b64_e32 v[16:17], 0
	v_mov_b64_e32 v[18:19], 0
	v_mov_b64_e32 v[20:21], 0
	v_mov_b64_e32 v[22:23], 0
	v_mov_b64_e32 v[24:25], 0
	v_mov_b64_e32 v[26:27], 0
	v_mov_b64_e32 v[28:29], 0
	v_mov_b64_e32 v[30:31], 0
	v_mov_b64_e32 v[32:33], 0
	v_mov_b64_e32 v[34:35], 0
	v_mov_b64_e32 v[36:37], 0
	v_mov_b64_e32 v[38:39], 0
	v_mov_b64_e32 v[40:41], 0
	v_mov_b64_e32 v[42:43], 0
	v_mov_b64_e32 v[44:45], 0
	v_mov_b64_e32 v[46:47], 0
	v_mov_b64_e32 v[48:49], 0
	v_mov_b64_e32 v[50:51], 0
	v_mov_b64_e32 v[52:53], 0
	v_mov_b64_e32 v[54:55], 0
	v_mov_b64_e32 v[56:57], 0
	v_mov_b64_e32 v[58:59], 0
	v_mov_b64_e32 v[60:61], 0
	v_mov_b64_e32 v[62:63], 0
	v_mov_b64_e32 v[64:65], 0
	v_mov_b64_e32 v[66:67], 0
	v_mov_b64_e32 v[68:69], 0
	v_mov_b64_e32 v[70:71], 0
	v_mov_b64_e32 v[72:73], 0
	v_mov_b64_e32 v[74:75], 0
	v_mov_b64_e32 v[76:77], 0
	v_mov_b64_e32 v[78:79], 0
	v_mov_b64_e32 v[80:81], 0
	v_mov_b64_e32 v[82:83], 0
	v_mov_b64_e32 v[84:85], 0
	v_mov_b64_e32 v[86:87], 0
	v_mov_b64_e32 v[88:89], 0
	v_mov_b64_e32 v[90:91], 0
	v_mov_b64_e32 v[92:93], 0
	v_mov_b64_e32 v[94:95], 0
	v_mov_b64_e32 v[96:97], 0
	v_mov_b64_e32 v[98:99], 0
	v_mov_b64_e32 v[100:101], 0
	v_mov_b64_e32 v[102:103], 0
	v_mov_b64_e32 v[104:105], 0
	v_mov_b64_e32 v[106:107], 0
	v_mov_b64_e32 v[108:109], 0
	v_mov_b64_e32 v[110:111], 0
	v_mov_b64_e32 v[112:113], 0
	v_mov_b64_e32 v[114:115], 0
	v_mov_b64_e32 v[116:117], 0
	v_mov_b64_e32 v[118:119], 0
	v_mov_b64_e32 v[120:121], 0
	v_mov_b64_e32 v[122:123], 0
	v_mov_b64_e32 v[124:125], 0
	v_mov_b64_e32 v[126:127], 0

; template <class Epi, bool HALO>
; __device__ __forceinline__ void gemm_phase(LAS unsigned char* lds, const bf16_t* Ag, const bf16_t* Btg, const int K, const int nM, const int nN, const int G, const int cidx, const int wave_, const Epi& E) {
;     ...
; #pragma unroll
;         for (int a = 0; a < 2; ++a)
; #pragma unroll
;             for (int b = 0; b < 2; ++b)
; #pragma unroll
;                 for (int m = 0; m < 4; ++m)
; #pragma unroll
;                     for (int n = 0; n < 2; ++n) acc[a][b][m][n] = (f32x4){0.f, 0.f, 0.f, 0.f};
;     __device__ __forceinline__ void operator()(const f32x4 (&acc)[2][2][4][2], const Unit& u, int wr, int wc, int fr, int fq) const {
;         int seqbase, t0, slen; halo_decode(u.pm, seqbase, t0, slen);
;         const f32x4* ct = (const f32x4*)(CT + (size_t)(128 * u.pn) * 8) + (32 * wc + 8 * fq) * 2;
;         const bool f0 = (fr == 0), f15 = (fr == 15);
; #pragma unroll
;         for (int ai = 0; ai < 2; ++ai) {
;             const int tbase = t0 + 62 * (2 * ai + wr) - 1;
;             float rs[4];
; #pragma unroll
;             for (int m = 0; m < 4; ++m) { const int t = tbase + 16 * m + fr; const bool vin = (t >= 0) && (t < slen); const int grow = seqbase + (vin ? t : 0);
;                 const f32x4 p = *(const f32x4*)(PS + (size_t)grow * 16 + 4 * fq); float s = (p[0] + p[1]) + (p[2] + p[3]); s = bfly_add<16>(s); s = bfly_add<32>(s); rs[m] = vin ? rsqrtf(s * (1.f / DM) + EPS) : 0.f; }
EC2_join:
	s_mul_i32 s86, s86, 0xf8
	s_bfe_u32 s89, s81, 0x10008
	s_mul_i32 s89, s89, 62
	s_add_i32 s89, s89, s86
	s_add_i32 s89, s89, -1
	v_mbcnt_lo_u32_b32 v176, -1, 0
	v_mbcnt_hi_u32_b32 v176, -1, v176
	v_and_b32_e32 v164, 15, v176
	v_lshlrev_b32_e32 v164, 2, v164
	v_bfe_u32 v165, v176, 4, 2
	v_lshlrev_b32_e32 v172, 8, v165
	v_lshlrev_b32_e32 v165, 4, v165
	v_add_u32_e32 v174, s89, v164
	v_lshrrev_b32_e32 v176, 4, v165
	v_add_u32_e32 v176, v176, v174
	v_cmp_gt_u32_e32 vcc, s91, v176
	s_nop 1
	v_cndmask_b32_e32 v176, 0, v176, vcc
	v_add_u32_e32 v176, s88, v176
	v_lshlrev_b32_e32 v252, 6, v176
	global_load_dwordx4 v[240:243], v252, s[70:71]
	global_load_dwordx4 v[244:247], v252, s[70:71] offset:16
	global_load_dwordx4 v[248:251], v252, s[70:71] offset:32
	global_load_dwordx4 v[160:163], v252, s[70:71] offset:48
	s_ashr_i32 s29, s28, 31
	s_lshl_b64 s[20:21], s[28:29], 19
	s_add_u32 s34, s38, s20
	s_addc_u32 s35, s39, s21
	s_and_b64 s[14:15], s[14:15], exec
	s_cselect_b32 s20, s35, s19
	s_cselect_b32 s21, s34, s18
	s_add_u32 s2, s2, 0x3e080
	s_addc_u32 s3, s3, 0
	s_add_u32 s29, s18, 0x100
	v_mov_b32_e32 v0, 0
	s_addc_u32 s37, s19, 0
	s_mov_b32 s51, -2
	v_mov_b64_e32 v[0:1], 0
	v_mov_b64_e32 v[2:3], 0
	v_mov_b64_e32 v[4:5], 0
	v_mov_b64_e32 v[6:7], 0
	v_mov_b64_e32 v[8:9], 0
	v_mov_b64_e32 v[10:11], 0
	v_mov_b64_e32 v[12:13], 0
	v_mov_b64_e32 v[14:15], 0
	v_mov_b64_e32 v[16:17], 0
	v_mov_b64_e32 v[18:19], 0
	v_mov_b64_e32 v[20:21], 0
	v_mov_b64_e32 v[22:23], 0
	v_mov_b64_e32 v[24:25], 0
	v_mov_b64_e32 v[26:27], 0
	v_mov_b64_e32 v[28:29], 0
	v_mov_b64_e32 v[30:31], 0
	v_mov_b64_e32 v[32:33], 0
	v_mov_b64_e32 v[34:35], 0
	v_mov_b64_e32 v[36:37], 0
	v_mov_b64_e32 v[38:39], 0
	v_mov_b64_e32 v[40:41], 0
	v_mov_b64_e32 v[42:43], 0
	v_mov_b64_e32 v[44:45], 0
	v_mov_b64_e32 v[46:47], 0
	v_mov_b64_e32 v[48:49], 0
	v_mov_b64_e32 v[50:51], 0
	v_mov_b64_e32 v[52:53], 0
	v_mov_b64_e32 v[54:55], 0
	v_mov_b64_e32 v[56:57], 0
	v_mov_b64_e32 v[58:59], 0
	v_mov_b64_e32 v[60:61], 0
	v_mov_b64_e32 v[62:63], 0
	v_mov_b64_e32 v[64:65], 0
	v_mov_b64_e32 v[66:67], 0
	v_mov_b64_e32 v[68:69], 0
	v_mov_b64_e32 v[70:71], 0
	v_mov_b64_e32 v[72:73], 0
	v_mov_b64_e32 v[74:75], 0
	v_mov_b64_e32 v[76:77], 0
	v_mov_b64_e32 v[78:79], 0
	v_mov_b64_e32 v[80:81], 0
	v_mov_b64_e32 v[82:83], 0
	v_mov_b64_e32 v[84:85], 0
	v_mov_b64_e32 v[86:87], 0
	v_mov_b64_e32 v[88:89], 0
	v_mov_b64_e32 v[90:91], 0
	v_mov_b64_e32 v[92:93], 0
	v_mov_b64_e32 v[94:95], 0
	v_mov_b64_e32 v[96:97], 0
	v_mov_b64_e32 v[98:99], 0
	v_mov_b64_e32 v[100:101], 0
	v_mov_b64_e32 v[102:103], 0
	v_mov_b64_e32 v[104:105], 0
	v_mov_b64_e32 v[106:107], 0
	v_mov_b64_e32 v[108:109], 0
	v_mov_b64_e32 v[110:111], 0
	v_mov_b64_e32 v[112:113], 0
	v_mov_b64_e32 v[114:115], 0
	v_mov_b64_e32 v[116:117], 0
	v_mov_b64_e32 v[118:119], 0
	v_mov_b64_e32 v[120:121], 0
	v_mov_b64_e32 v[122:123], 0
	v_mov_b64_e32 v[124:125], 0
	v_mov_b64_e32 v[126:127], 0

; template <class Epi, bool HALO>
; __device__ __forceinline__ void gemm_phase(LAS unsigned char* lds, const bf16_t* Ag, const bf16_t* Btg, const int K, const int nM, const int nN, const int G, const int cidx, const int wave_, const Epi& E) {
;     ...
; #pragma unroll
;         for (int a = 0; a < 2; ++a)
; #pragma unroll
;             for (int b = 0; b < 2; ++b)
; #pragma unroll
;                 for (int m = 0; m < 4; ++m)
; #pragma unroll
;                     for (int n = 0; n < 2; ++n) acc[a][b][m][n] = (f32x4){0.f, 0.f, 0.f, 0.f};
.LBB0_878:
	s_add_u32 s46, s26, 0x100
	v_mov_b32_e32 v0, 0
	s_addc_u32 s47, s27, 0
	s_mov_b32 s48, -2
	v_mov_b64_e32 v[0:1], 0
	v_mov_b64_e32 v[2:3], 0
	v_mov_b64_e32 v[4:5], 0
	v_mov_b64_e32 v[6:7], 0
	v_mov_b64_e32 v[8:9], 0
	v_mov_b64_e32 v[10:11], 0
	v_mov_b64_e32 v[12:13], 0
	v_mov_b64_e32 v[14:15], 0
	v_mov_b64_e32 v[16:17], 0
	v_mov_b64_e32 v[18:19], 0
	v_mov_b64_e32 v[20:21], 0
	v_mov_b64_e32 v[22:23], 0
	v_mov_b64_e32 v[24:25], 0
	v_mov_b64_e32 v[26:27], 0
	v_mov_b64_e32 v[28:29], 0
	v_mov_b64_e32 v[30:31], 0
	v_mov_b64_e32 v[32:33], 0
	v_mov_b64_e32 v[34:35], 0
	v_mov_b64_e32 v[36:37], 0
	v_mov_b64_e32 v[38:39], 0
	v_mov_b64_e32 v[40:41], 0
	v_mov_b64_e32 v[42:43], 0
	v_mov_b64_e32 v[44:45], 0
	v_mov_b64_e32 v[46:47], 0
	v_mov_b64_e32 v[48:49], 0
	v_mov_b64_e32 v[50:51], 0
	v_mov_b64_e32 v[52:53], 0
	v_mov_b64_e32 v[54:55], 0
	v_mov_b64_e32 v[56:57], 0
	v_mov_b64_e32 v[58:59], 0
	v_mov_b64_e32 v[60:61], 0
	v_mov_b64_e32 v[62:63], 0
	v_mov_b64_e32 v[64:65], 0
	v_mov_b64_e32 v[66:67], 0
	v_mov_b64_e32 v[68:69], 0
	v_mov_b64_e32 v[70:71], 0
	v_mov_b64_e32 v[72:73], 0
	v_mov_b64_e32 v[74:75], 0
	v_mov_b64_e32 v[76:77], 0
	v_mov_b64_e32 v[78:79], 0
	v_mov_b64_e32 v[80:81], 0
	v_mov_b64_e32 v[82:83], 0
	v_mov_b64_e32 v[84:85], 0
	v_mov_b64_e32 v[86:87], 0
	v_mov_b64_e32 v[88:89], 0
	v_mov_b64_e32 v[90:91], 0
	v_mov_b64_e32 v[92:93], 0
	v_mov_b64_e32 v[94:95], 0
	v_mov_b64_e32 v[96:97], 0
	v_mov_b64_e32 v[98:99], 0
	v_mov_b64_e32 v[100:101], 0
	v_mov_b64_e32 v[102:103], 0
	v_mov_b64_e32 v[104:105], 0
	v_mov_b64_e32 v[106:107], 0
	v_mov_b64_e32 v[108:109], 0
	v_mov_b64_e32 v[110:111], 0
	v_mov_b64_e32 v[112:113], 0
	v_mov_b64_e32 v[114:115], 0
	v_mov_b64_e32 v[116:117], 0
	v_mov_b64_e32 v[118:119], 0
	v_mov_b64_e32 v[120:121], 0
	v_mov_b64_e32 v[122:123], 0
	v_mov_b64_e32 v[124:125], 0
	v_mov_b64_e32 v[126:127], 0
